# same without the P5 staging-load parallelisation
# speedup vs baseline: 1.0420x; 1.0084x over previous
.LBB0_1393:
	s_lshr_b32 s0, s5, 5
	s_and_b32 s1, s5, 31
	s_lshr_b32 s97, s1, 4
	s_lshl_b32 s97, s97, 2
	s_and_b32 s2, s0, 3
	s_or_b32 s97, s97, s2
	s_lshr_b32 s0, s0, 2
	s_lshl_b32 s0, s0, 4
	s_and_b32 s1, s1, 15
	s_or_b32 s0, s0, s1
	s_lshl_b32 s88, s0, 8
	s_cmp_lt_i32 s0, 64
	s_movk_i32 s0, 0xe000
	s_cselect_b32 s0, s0, 0x7ffff000
	s_movk_i32 s1, 0x2000
	s_cselect_b32 s2, s1, 0x1000
	s_and_b32 s33, s0, s88
	s_sub_i32 s3, s88, s33
	s_sub_i32 s0, s3, 64
	s_add_i32 s1, s2, -1
	v_add_u32_e32 v0, s0, v91
	v_min_i32_e32 v1, s1, v0
	v_cmp_lt_i32_e32 vcc, -1, v0
	s_lshl_b32 s89, s97, 7
	v_or_b32_e32 v148, s89, v90
	v_cndmask_b32_e32 v0, 0, v1, vcc
	v_add_u32_e32 v0, s33, v0
	v_lshl_add_u32 v24, v0, 10, v148
	v_add_u32_e32 v0, s0, v92
	v_min_i32_e32 v1, s1, v0
	v_cmp_lt_i32_e32 vcc, -1, v0
	v_add_u32_e32 v8, s0, v93
	v_min_i32_e32 v9, s1, v8
	v_cndmask_b32_e32 v0, 0, v1, vcc
	v_cmp_lt_i32_e32 vcc, -1, v8
	v_add_u32_e32 v16, s0, v95
	v_min_i32_e32 v17, s1, v16
	v_cndmask_b32_e32 v8, 0, v9, vcc
	v_add_u32_e32 v8, s33, v8
	v_lshl_add_u32 v26, v8, 10, v148
	v_add_u32_e32 v8, s0, v94
	v_min_i32_e32 v9, s1, v8
	v_cmp_lt_i32_e32 vcc, -1, v8
	v_add_u32_e32 v0, s33, v0
	v_lshl_add_u32 v25, v0, 10, v148
	v_cndmask_b32_e32 v8, 0, v9, vcc
	v_cmp_lt_i32_e32 vcc, -1, v16
	v_add_u32_e32 v8, s33, v8
	global_load_dwordx4 v[0:3], v24, s[92:93]
	global_load_dwordx4 v[4:7], v25, s[92:93]
	v_cndmask_b32_e32 v16, 0, v17, vcc
	v_add_u32_e32 v16, s33, v16
	v_lshl_add_u32 v28, v16, 10, v148
	v_add_u32_e32 v16, s0, v97
	v_min_i32_e32 v17, s1, v16
	v_cmp_lt_i32_e32 vcc, -1, v16
	v_lshl_add_u32 v27, v8, 10, v148
	global_load_dwordx4 v[8:11], v26, s[92:93]
	global_load_dwordx4 v[12:15], v27, s[92:93]
	v_cndmask_b32_e32 v16, 0, v17, vcc
	v_or_b32_e32 v17, s33, v96
	v_add_u32_e32 v16, v17, v16
	v_lshl_add_u32 v29, v16, 10, v148
	global_load_dwordx4 v[16:19], v28, s[92:93]
	global_load_dwordx4 v[20:23], v29, s[92:93]
	global_load_dword v30, v[76:77], off
	global_load_dword v31, v[78:79], off
	v_readlane_b32 s0, v243, 3
	s_add_i32 s0, s3, s0
	v_or_b32_e32 v149, s89, v100
	s_mov_b32 s38, 0
	v_mov_b32_e32 v56, 0
	v_mov_b32_e32 v57, v75
	s_waitcnt vmcnt(0)
	ds_write_b128 v138, v[0:3]
	ds_write_b128 v139, v[4:7]
	ds_write_b128 v138, v[8:11] offset:18432
	ds_write_b128 v140, v[12:15]
	ds_write_b128 v138, v[16:19] offset:36864
	ds_write_b128 v141, v[20:23]
	global_load_dwordx4 v[0:3], v24, s[94:95]
	global_load_dwordx4 v[4:7], v25, s[94:95]
	global_load_dwordx4 v[8:11], v26, s[94:95]
	global_load_dwordx4 v[12:15], v27, s[94:95]
	global_load_dwordx4 v[16:19], v28, s[94:95]
	global_load_dwordx4 v[20:23], v29, s[94:95]
	v_or_b32_e32 v24, s0, v73
	v_or_b32_e32 v25, s0, v72
	v_add_u32_e32 v26, s33, v24
	v_add_u32_e32 v27, s33, v25
	v_lshl_add_u32 v26, v26, 10, v149
	v_lshl_add_u32 v27, v27, 10, v149
	v_or_b32_e32 v36, 64, v26
	v_or_b32_e32 v44, 64, v27
	v_and_b32_e32 v28, 0x7fffffff, v30
	v_and_b32_e32 v29, 0x7fffffff, v31
	ds_bpermute_b32 v28, v81, v28
	ds_bpermute_b32 v29, v81, v29
	v_max_f32_e64 v30, |v30|, |v30|
	v_max_f32_e64 v31, |v31|, |v31|
	s_mul_i32 s0, s97, 0xc000
	s_waitcnt lgkmcnt(1)
	v_max_f32_e32 v28, v28, v28
	s_waitcnt lgkmcnt(0)
	v_max_f32_e32 v29, v29, v29
	v_max_f32_e32 v28, v30, v28
	v_max_f32_e32 v29, v31, v29
	ds_bpermute_b32 v30, v85, v28
	ds_bpermute_b32 v31, v85, v29
	s_waitcnt vmcnt(5)
	ds_write_b128 v138, v[0:3] offset:55296
	s_waitcnt vmcnt(4)
	ds_write_b128 v139, v[4:7] offset:55296
	s_waitcnt vmcnt(3)
	ds_write_b128 v98, v[8:11]
	s_waitcnt vmcnt(2)
	ds_write_b128 v140, v[12:15] offset:55296
	s_waitcnt vmcnt(1)
	ds_write_b128 v99, v[16:19]
	s_waitcnt vmcnt(0)
	ds_write_b128 v141, v[20:23] offset:55296
	s_waitcnt lgkmcnt(0)
	s_barrier
	global_load_dwordx4 v[32:35], v26, s[90:91]
	s_nop 0
	global_load_dwordx4 v[36:39], v36, s[90:91]
	s_nop 0
	global_load_dwordx4 v[40:43], v27, s[90:91]
	s_nop 0
	global_load_dwordx4 v[44:47], v44, s[90:91]
	s_waitcnt lgkmcnt(7)
	v_max_f32_e32 v30, v30, v30
	s_waitcnt lgkmcnt(6)
	v_max_f32_e32 v31, v31, v31
	v_max_f32_e32 v28, v28, v30
	v_max_f32_e32 v29, v29, v31
	ds_bpermute_b32 v30, v86, v28
	ds_bpermute_b32 v31, v86, v29
	v_mov_b32_e32 v4, 0
	v_mov_b32_e32 v5, v75
	v_mov_b32_e32 v6, v75
	s_waitcnt lgkmcnt(1)
	v_max_f32_e32 v0, v30, v30
	v_max_f32_e32 v0, v28, v0
	s_waitcnt lgkmcnt(0)
	v_max_f32_e32 v2, v31, v31
	ds_bpermute_b32 v1, v87, v0
	v_max_f32_e32 v2, v29, v2
	ds_bpermute_b32 v3, v87, v2
	v_mov_b32_e32 v7, v75
	v_mov_b32_e32 v8, 0
	s_waitcnt lgkmcnt(1)
	v_max_f32_e32 v1, v1, v1
	v_max_f32_e32 v0, v0, v1
	s_waitcnt lgkmcnt(0)
	v_max_f32_e32 v3, v3, v3
	ds_bpermute_b32 v1, v88, v0
	v_max_f32_e32 v2, v2, v3
	ds_bpermute_b32 v3, v88, v2
	v_mov_b32_e32 v9, v75
	v_mov_b32_e32 v10, v75
	s_waitcnt lgkmcnt(1)
	v_max_f32_e32 v1, v1, v1
	v_max_f32_e32 v0, v0, v1
	s_waitcnt lgkmcnt(0)
	v_max_f32_e32 v3, v3, v3
	ds_bpermute_b32 v1, v89, v0
	v_max_f32_e32 v2, v2, v3
	ds_bpermute_b32 v3, v89, v2
	v_mov_b32_e32 v11, v75
	v_mov_b32_e32 v12, 0
	s_waitcnt lgkmcnt(1)
	v_max_f32_e32 v1, v1, v1
	v_max_f32_e32 v0, v0, v1
	s_waitcnt lgkmcnt(0)
	v_max_f32_e32 v1, v3, v3
	v_max_f32_e32 v1, v2, v1
	v_mul_f32_e32 v0, 0x41000000, v0
	v_mul_f32_e32 v0, v0, v1
	v_mul_f32_e32 v150, 0x3fb8aa3b, v0
	v_max_i32_e32 v0, 64, v25
	v_max_i32_e32 v1, 64, v24
	v_subrev_u32_e32 v52, 64, v0
	v_add_u32_e32 v0, 64, v24
	v_subrev_u32_e32 v53, 64, v1
	v_min_i32_e32 v0, s1, v0
	v_add_u32_e32 v1, 64, v25
	v_sub_u32_e32 v55, v0, v53
	v_add_u32_e32 v0, s88, v125
	v_min_i32_e32 v1, s1, v1
	v_subrev_u32_e32 v0, s33, v0
	v_sub_u32_e32 v54, v1, v52
	v_mov_b32_e32 v70, v0
	v_mov_b32_e32 v0, 0
	v_mov_b32_e32 v1, v75
	v_mov_b32_e32 v2, v75
	v_mov_b32_e32 v3, v75
	v_mov_b32_e32 v13, v75
	v_mov_b32_e32 v14, v75
	v_mov_b32_e32 v15, v75
	v_mov_b32_e32 v16, 0
	v_mov_b32_e32 v17, v75
	v_mov_b32_e32 v18, v75
	v_mov_b32_e32 v19, v75
	v_mov_b32_e32 v20, 0
	v_mov_b32_e32 v21, v75
	v_mov_b32_e32 v22, v75
	v_mov_b32_e32 v23, v75
	v_mov_b32_e32 v24, 0
	v_mov_b32_e32 v25, v75
	v_mov_b32_e32 v26, v75
	v_mov_b32_e32 v27, v75
	v_mov_b32_e32 v28, 0
	v_mov_b32_e32 v29, v75
	v_mov_b32_e32 v30, v75
	v_mov_b32_e32 v31, v75

.LBB0_1577:
	v_lshl_add_u64 v[72:73], v[154:155], 0, s[94:95]
	s_barrier
	global_load_dword v110, v[146:147], off
	global_load_ushort v233, v[72:73], off offset:-2048
	global_load_ushort v231, v[72:73], off offset:-2016
	global_load_ushort v229, v[72:73], off offset:-1984
	global_load_ushort v227, v[72:73], off offset:-1952
	global_load_ushort v234, v[72:73], off offset:-1024
	global_load_ushort v232, v[72:73], off offset:-992
	global_load_ushort v230, v[72:73], off offset:-960
	global_load_ushort v228, v[72:73], off offset:-928
	global_load_ushort v225, v[72:73], off
	global_load_ushort v223, v[72:73], off offset:32
	global_load_ushort v221, v[72:73], off offset:64
	global_load_ushort v219, v[72:73], off offset:96
	global_load_ushort v226, v[72:73], off offset:1024
	global_load_ushort v224, v[72:73], off offset:1056
	global_load_ushort v222, v[72:73], off offset:1088
	global_load_ushort v220, v[72:73], off offset:1120
	v_add_u32_e32 v72, v188, v176
	v_add_u32_e32 v73, v188, v177
	s_waitcnt vmcnt(21)
	ds_write_b128 v206, v[48:51]
	s_waitcnt vmcnt(20)
	ds_write_b128 v207, v[52:55]
	s_waitcnt vmcnt(19)
	ds_write_b128 v72, v[56:59]
	s_waitcnt vmcnt(18)
	ds_write_b128 v73, v[60:63]
	s_waitcnt vmcnt(17)
	ds_write_b128 v72, v[64:67] offset:17408
	v_add_u32_e32 v72, v188, v178
	s_cmpk_eq_i32 s94, 0x180
	s_waitcnt vmcnt(16)
	ds_write_b128 v72, v[68:71]
	s_cbranch_scc1 .LBB0_1579
	v_readlane_b32 s4, v244, 0
	s_ashr_i32 s93, s92, 31
	v_readlane_b32 s5, v244, 1
	v_readlane_b32 s6, v244, 2
	v_readlane_b32 s7, v244, 3
	v_readlane_b32 s8, v244, 4
	v_readlane_b32 s9, v244, 5
	s_lshl_b64 s[96:97], s[92:93], 14
	v_readlane_b32 s10, v244, 6
	v_readlane_b32 s11, v244, 7
	s_mov_b64 s[4:5], s[8:9]
	s_add_u32 s96, s4, s96
	s_addc_u32 s97, s5, s97
	v_lshl_add_u64 v[56:57], s[96:97], 0, v[120:121]
	v_add_co_u32_e32 v58, vcc, 0x2000, v56
	v_lshl_add_u64 v[48:49], v[152:153], 0, s[94:95]
	v_lshl_add_u64 v[50:51], v[150:151], 0, s[94:95]
	v_addc_co_u32_e32 v59, vcc, 0, v57, vcc
	global_load_dwordx4 v[52:55], v[50:51], off
	global_load_dwordx4 v[60:63], v[58:59], off
	s_nop 0
	global_load_dwordx4 v[48:51], v[48:49], off
	s_nop 0
	global_load_dwordx4 v[64:67], v205, s[96:97]
	v_add_co_u32_e32 v68, vcc, 0x6000, v56
	s_mov_b64 s[6:7], s[10:11]
	s_nop 0
	v_addc_co_u32_e32 v69, vcc, 0, v57, vcc
	global_load_dwordx4 v[56:59], v120, s[96:97]
	s_nop 0
	global_load_dwordx4 v[68:71], v[68:69], off
.LBB0_1579:
	s_waitcnt lgkmcnt(0)
	s_waitcnt lgkmcnt(0)
	s_barrier
	s_nop 0
	v_add_u32_e32 v72, 0, v133
	ds_read2st64_b32 v[100:101], v72 offset1:2
	s_add_i32 s1, s0, 0
	v_mov_b32_e32 v72, s1
	v_add_u32_e32 v79, 0, v135
	ds_read_b128 v[80:83], v79 offset:4096
	ds_read_b32 v165, v72
	ds_read_b128 v[72:75], v79
	s_mov_b64 s[96:97], -1
	s_andn2_b64 vcc, exec, s[2:3]
	s_waitcnt lgkmcnt(2)
	v_sub_f32_e32 v80, v100, v80
	v_sub_f32_e32 v78, v100, v81
	v_sub_f32_e32 v77, v100, v82
	v_sub_f32_e32 v76, v100, v83
	s_cbranch_vccnz .LBB0_1581
	v_min_f32_e32 v81, 0, v80
	v_mul_f32_e32 v81, 0x3fb8aa3b, v81
	v_exp_f32_e32 v82, v81
	v_min_f32_e32 v81, 0, v78
	v_mul_f32_e32 v81, 0x3fb8aa3b, v81
	v_exp_f32_e32 v83, v81
	v_min_f32_e32 v81, 0, v77
	v_mul_f32_e32 v81, 0x3fb8aa3b, v81
	v_exp_f32_e32 v86, v81
	v_min_f32_e32 v81, 0, v76
	v_mul_f32_e32 v81, 0x3fb8aa3b, v81
	v_exp_f32_e32 v87, v81
	s_waitcnt lgkmcnt(0)
	v_pk_mul_f32 v[82:83], v[72:73], v[82:83]
	s_mov_b64 s[96:97], 0
	v_pk_mul_f32 v[84:85], v[16:17], v[82:83]
	v_pk_mul_f32 v[82:83], v[74:75], v[86:87]
	s_nop 0
	v_pk_mul_f32 v[86:87], v[18:19], v[82:83]
.LBB0_1581:
	s_andn2_b64 vcc, exec, s[96:97]
	s_cbranch_vccnz .LBB0_1583
	ds_read_b128 v[84:87], v79 offset:4608
	v_min_f32_e32 v80, 0, v80
	v_mul_f32_e32 v80, 0x3fb8aa3b, v80
	v_exp_f32_e32 v88, v80
	ds_read_b128 v[80:83], v79 offset:512
	s_waitcnt lgkmcnt(1)
	v_sub_f32_e32 v79, v84, v101
	v_min_f32_e32 v79, 0, v79
	v_mul_f32_e32 v79, 0x3fb8aa3b, v79
	v_exp_f32_e32 v84, v79
	v_sub_f32_e32 v79, v85, v101
	v_min_f32_e32 v78, 0, v78
	v_min_f32_e32 v79, 0, v79
	v_mul_f32_e32 v78, 0x3fb8aa3b, v78
	v_mul_f32_e32 v79, 0x3fb8aa3b, v79
	v_exp_f32_e32 v78, v78
	v_exp_f32_e32 v85, v79
	v_mul_f32_e32 v72, v72, v88
	v_cndmask_b32_e64 v72, v72, 0, s[18:19]
	v_mul_f32_e32 v73, v73, v78
	s_waitcnt lgkmcnt(0)
	v_pk_mul_f32 v[78:79], v[80:81], v[84:85]
	v_cndmask_b32_e64 v73, 0, v73, s[16:17]
	v_cndmask_b32_e64 v79, v79, 0, s[20:21]
	v_cndmask_b32_e64 v78, v78, 0, s[16:17]
	v_pk_add_f32 v[72:73], v[72:73], v[78:79]
	v_sub_f32_e32 v78, v86, v101
	v_min_f32_e32 v78, 0, v78
	v_min_f32_e32 v77, 0, v77
	v_mul_f32_e32 v78, 0x3fb8aa3b, v78
	v_mul_f32_e32 v77, 0x3fb8aa3b, v77
	v_exp_f32_e32 v78, v78
	v_exp_f32_e32 v77, v77
	s_nop 0
	v_cndmask_b32_e64 v88, 0, v110, s[24:25]
	v_cndmask_b32_e64 v89, 0, v110, s[22:23]
	v_pk_fma_f32 v[84:85], v[16:17], v[72:73], v[88:89]
	v_mul_f32_e32 v73, v82, v78
	v_mul_f32_e32 v72, v74, v77
	v_cndmask_b32_e64 v74, v73, 0, s[28:29]
	v_min_f32_e32 v73, 0, v76
	v_mul_f32_e32 v73, 0x3fb8aa3b, v73
	v_exp_f32_e32 v76, v73
	v_sub_f32_e32 v73, v87, v101
	v_min_f32_e32 v73, 0, v73
	v_mul_f32_e32 v73, 0x3fb8aa3b, v73
	v_exp_f32_e32 v77, v73
	v_mov_b32_e32 v82, v75
	v_cndmask_b32_e64 v72, v72, 0, s[26:27]
	v_cndmask_b32_e64 v78, 0, v110, s[38:39]
	v_pk_mul_f32 v[76:77], v[82:83], v[76:77]
	v_cndmask_b32_e64 v79, 0, v110, s[36:37]
	v_cndmask_b32_e64 v75, v77, 0, s[30:31]
	v_cndmask_b32_e64 v73, v76, 0, s[34:35]
	v_pk_add_f32 v[72:73], v[72:73], v[74:75]
	s_nop 0
	v_pk_fma_f32 v[86:87], v[18:19], v[72:73], v[78:79]

.LBB0_1586:
	s_andn2_b64 vcc, exec, s[96:97]
	s_cbranch_vccnz .LBB0_1588
	v_min_f32_e32 v89, 0, v95
	v_mul_f32_e32 v89, 0x3fb8aa3b, v89
	v_sub_f32_e32 v88, v100, v76
	v_exp_f32_e32 v90, v89
	v_sub_f32_e32 v89, v100, v77
	v_min_f32_e32 v88, 0, v88
	v_min_f32_e32 v89, 0, v89
	v_mul_f32_e32 v88, 0x3fb8aa3b, v88
	v_readlane_b32 s4, v244, 61
	v_mul_f32_e32 v89, 0x3fb8aa3b, v89
	v_exp_f32_e32 v88, v88
	v_readlane_b32 s5, v244, 62
	v_exp_f32_e32 v89, v89
	v_min_f32_e32 v91, 0, v94
	s_nop 0
	v_cndmask_b32_e64 v96, 0, v110, s[4:5]
	v_readlane_b32 s4, v243, 1
	v_readlane_b32 s5, v243, 2
	v_mul_f32_e32 v91, 0x3fb8aa3b, v91
	v_exp_f32_e32 v91, v91
	v_cndmask_b32_e64 v97, 0, v110, s[4:5]
	v_readlane_b32 s4, v243, 3
	v_pk_mul_f32 v[88:89], v[72:73], v[88:89]
	v_readlane_b32 s5, v243, 4
	s_waitcnt lgkmcnt(0)
	v_pk_mul_f32 v[80:81], v[80:81], v[90:91]
	v_cndmask_b32_e64 v89, v89, 0, s[4:5]
	v_readlane_b32 s4, v243, 7
	v_readlane_b32 s5, v243, 8
	s_nop 1
	v_cndmask_b32_e64 v88, v88, 0, s[4:5]
	v_readlane_b32 s4, v244, 57
	v_readlane_b32 s5, v244, 58
	s_nop 1
	v_cndmask_b32_e64 v81, v81, 0, s[4:5]
	v_readlane_b32 s4, v244, 59
	v_readlane_b32 s5, v244, 60
	s_nop 1
	v_cndmask_b32_e64 v80, v80, 0, s[4:5]
	v_pk_add_f32 v[80:81], v[88:89], v[80:81]
	v_sub_f32_e32 v88, v100, v78
	v_min_f32_e32 v88, 0, v88
	v_mul_f32_e32 v88, 0x3fb8aa3b, v88
	v_exp_f32_e32 v90, v88
	v_min_f32_e32 v88, 0, v93
	v_mul_f32_e32 v88, 0x3fb8aa3b, v88
	v_exp_f32_e32 v91, v88
	v_readlane_b32 s4, v244, 63
	v_pk_fma_f32 v[88:89], v[20:21], v[80:81], v[96:97]
	v_mul_f32_e32 v80, v74, v90
	v_readlane_b32 s5, v243, 0
	v_mul_f32_e32 v81, v82, v91
	v_mov_b32_e32 v82, v75
	v_cndmask_b32_e64 v80, v80, 0, s[4:5]
	v_readlane_b32 s4, v243, 10
	v_readlane_b32 s5, v243, 11
	s_nop 1
	v_cndmask_b32_e64 v90, v81, 0, s[4:5]
	v_sub_f32_e32 v81, v100, v79
	v_min_f32_e32 v81, 0, v81
	v_mul_f32_e32 v81, 0x3fb8aa3b, v81
	v_exp_f32_e32 v94, v81
	v_min_f32_e32 v81, 0, v92
	v_mul_f32_e32 v81, 0x3fb8aa3b, v81
	v_readlane_b32 s4, v243, 36
	v_exp_f32_e32 v95, v81
	v_readlane_b32 s5, v243, 37
	v_pk_mul_f32 v[82:83], v[82:83], v[94:95]
	s_nop 0
	v_cndmask_b32_e64 v92, 0, v110, s[4:5]
	v_readlane_b32 s4, v243, 34
	v_readlane_b32 s5, v243, 35
	s_nop 1
	v_cndmask_b32_e64 v93, 0, v110, s[4:5]
	v_readlane_b32 s4, v244, 52
	v_readlane_b32 s5, v244, 53
	s_nop 1
	v_cndmask_b32_e64 v91, v83, 0, s[4:5]
	v_readlane_b32 s4, v243, 5
	v_readlane_b32 s5, v243, 6
	s_nop 1
	v_cndmask_b32_e64 v81, v82, 0, s[4:5]
	v_pk_add_f32 v[80:81], v[80:81], v[90:91]
	s_nop 0
	v_pk_fma_f32 v[90:91], v[22:23], v[80:81], v[92:93]

.LBB0_1594:
	s_andn2_b64 vcc, exec, s[96:97]
	s_cbranch_vccnz .LBB0_1596
	v_min_f32_e32 v103, 0, v109
	v_mul_f32_e32 v103, 0x3fb8aa3b, v103
	v_sub_f32_e32 v102, v100, v92
	v_exp_f32_e32 v104, v103
	v_sub_f32_e32 v103, v100, v93
	v_min_f32_e32 v102, 0, v102
	v_min_f32_e32 v103, 0, v103
	v_mul_f32_e32 v102, 0x3fb8aa3b, v102
	v_readlane_b32 s4, v243, 48
	v_mul_f32_e32 v103, 0x3fb8aa3b, v103
	v_exp_f32_e32 v102, v102
	v_readlane_b32 s5, v243, 49
	v_exp_f32_e32 v103, v103
	v_min_f32_e32 v105, 0, v108
	s_nop 0
	v_cndmask_b32_e64 v112, 0, v110, s[4:5]
	v_readlane_b32 s4, v243, 46
	v_readlane_b32 s5, v243, 47
	v_mul_f32_e32 v105, 0x3fb8aa3b, v105
	v_exp_f32_e32 v105, v105
	v_cndmask_b32_e64 v113, 0, v110, s[4:5]
	v_readlane_b32 s4, v243, 38
	v_pk_mul_f32 v[102:103], v[88:89], v[102:103]
	v_readlane_b32 s5, v243, 39
	s_waitcnt lgkmcnt(0)
	v_pk_mul_f32 v[96:97], v[96:97], v[104:105]
	v_cndmask_b32_e64 v103, v103, 0, s[4:5]
	v_readlane_b32 s4, v243, 40
	v_readlane_b32 s5, v243, 41
	s_nop 1
	v_cndmask_b32_e64 v102, v102, 0, s[4:5]
	v_readlane_b32 s4, v243, 42
	v_readlane_b32 s5, v243, 43
	s_nop 1
	v_cndmask_b32_e64 v97, v97, 0, s[4:5]
	v_readlane_b32 s4, v243, 44
	v_readlane_b32 s5, v243, 45
	s_nop 1
	v_cndmask_b32_e64 v96, v96, 0, s[4:5]
	v_pk_add_f32 v[96:97], v[102:103], v[96:97]
	v_sub_f32_e32 v102, v100, v94
	v_min_f32_e32 v102, 0, v102
	v_mul_f32_e32 v102, 0x3fb8aa3b, v102
	v_exp_f32_e32 v104, v102
	v_min_f32_e32 v102, 0, v107
	v_mul_f32_e32 v102, 0x3fb8aa3b, v102
	v_exp_f32_e32 v105, v102
	v_readlane_b32 s4, v243, 50
	v_pk_fma_f32 v[102:103], v[24:25], v[96:97], v[112:113]
	v_mul_f32_e32 v96, v90, v104
	v_readlane_b32 s5, v243, 51
	v_mul_f32_e32 v97, v98, v105
	v_mov_b32_e32 v98, v91
	v_cndmask_b32_e64 v96, v96, 0, s[4:5]
	v_readlane_b32 s4, v243, 52
	v_readlane_b32 s5, v243, 53
	s_nop 1
	v_cndmask_b32_e64 v104, v97, 0, s[4:5]
	v_sub_f32_e32 v97, v100, v95
	v_min_f32_e32 v97, 0, v97
	v_mul_f32_e32 v97, 0x3fb8aa3b, v97
	v_exp_f32_e32 v108, v97
	v_min_f32_e32 v97, 0, v106
	v_mul_f32_e32 v97, 0x3fb8aa3b, v97
	v_readlane_b32 s4, v243, 60
	v_exp_f32_e32 v109, v97
	v_readlane_b32 s5, v243, 61
	v_pk_mul_f32 v[98:99], v[98:99], v[108:109]
	s_nop 0
	v_cndmask_b32_e64 v106, 0, v110, s[4:5]
	v_readlane_b32 s4, v243, 58
	v_readlane_b32 s5, v243, 59
	s_nop 1
	v_cndmask_b32_e64 v107, 0, v110, s[4:5]
	v_readlane_b32 s4, v243, 54
	v_readlane_b32 s5, v243, 55
	s_nop 1
	v_cndmask_b32_e64 v105, v99, 0, s[4:5]
	v_readlane_b32 s4, v243, 56
	v_readlane_b32 s5, v243, 57
	s_nop 1
	v_cndmask_b32_e64 v97, v98, 0, s[4:5]
	v_pk_add_f32 v[96:97], v[96:97], v[104:105]
	s_nop 0
	v_pk_fma_f32 v[104:105], v[26:27], v[96:97], v[106:107]

.LBB0_1602:
	s_andn2_b64 vcc, exec, s[96:97]
	s_cbranch_vccnz .LBB0_1604
	v_min_f32_e32 v107, 0, v114
	v_mul_f32_e32 v107, 0x3fb8aa3b, v107
	v_sub_f32_e32 v106, v100, v92
	v_exp_f32_e32 v108, v107
	v_sub_f32_e32 v107, v100, v93
	v_min_f32_e32 v106, 0, v106
	v_min_f32_e32 v107, 0, v107
	v_mul_f32_e32 v106, 0x3fb8aa3b, v106
	v_readlane_b32 s4, v242, 8
	v_mul_f32_e32 v107, 0x3fb8aa3b, v107
	v_exp_f32_e32 v106, v106
	v_readlane_b32 s5, v242, 9
	v_exp_f32_e32 v107, v107
	v_min_f32_e32 v109, 0, v113
	s_nop 0
	v_cndmask_b32_e64 v114, 0, v110, s[4:5]
	v_readlane_b32 s4, v242, 6
	v_readlane_b32 s5, v242, 7
	v_mul_f32_e32 v109, 0x3fb8aa3b, v109
	v_exp_f32_e32 v109, v109
	v_cndmask_b32_e64 v115, 0, v110, s[4:5]
	v_readlane_b32 s4, v243, 62
	v_pk_mul_f32 v[106:107], v[88:89], v[106:107]
	v_readlane_b32 s5, v243, 63
	s_waitcnt lgkmcnt(0)
	v_pk_mul_f32 v[96:97], v[96:97], v[108:109]
	v_cndmask_b32_e64 v107, v107, 0, s[4:5]
	v_readlane_b32 s4, v242, 0
	v_readlane_b32 s5, v242, 1
	s_nop 1
	v_cndmask_b32_e64 v106, v106, 0, s[4:5]
	v_readlane_b32 s4, v242, 2
	v_readlane_b32 s5, v242, 3
	s_nop 1
	v_cndmask_b32_e64 v97, v97, 0, s[4:5]
	v_readlane_b32 s4, v242, 4
	v_readlane_b32 s5, v242, 5
	s_nop 1
	v_cndmask_b32_e64 v96, v96, 0, s[4:5]
	v_pk_add_f32 v[96:97], v[106:107], v[96:97]
	v_sub_f32_e32 v106, v100, v94
	v_min_f32_e32 v106, 0, v106
	v_mul_f32_e32 v106, 0x3fb8aa3b, v106
	v_exp_f32_e32 v108, v106
	v_min_f32_e32 v106, 0, v112
	v_mul_f32_e32 v106, 0x3fb8aa3b, v106
	v_exp_f32_e32 v109, v106
	v_readlane_b32 s4, v242, 10
	v_pk_fma_f32 v[106:107], v[28:29], v[96:97], v[114:115]
	v_mul_f32_e32 v96, v90, v108
	v_readlane_b32 s5, v242, 11
	v_mul_f32_e32 v97, v98, v109
	v_mov_b32_e32 v98, v91
	v_cndmask_b32_e64 v96, v96, 0, s[4:5]
	v_readlane_b32 s4, v242, 12
	v_readlane_b32 s5, v242, 13
	s_nop 1
	v_cndmask_b32_e64 v108, v97, 0, s[4:5]
	v_sub_f32_e32 v97, v100, v95
	v_min_f32_e32 v97, 0, v97
	v_mul_f32_e32 v97, 0x3fb8aa3b, v97
	v_exp_f32_e32 v112, v97
	v_min_f32_e32 v97, 0, v111
	v_mul_f32_e32 v97, 0x3fb8aa3b, v97
	v_readlane_b32 s4, v242, 20
	v_exp_f32_e32 v113, v97
	v_readlane_b32 s5, v242, 21
	v_pk_mul_f32 v[98:99], v[98:99], v[112:113]
	s_nop 0
	v_cndmask_b32_e64 v114, 0, v110, s[4:5]
	v_readlane_b32 s4, v242, 18
	v_readlane_b32 s5, v242, 19
	s_nop 1
	v_cndmask_b32_e64 v115, 0, v110, s[4:5]
	v_readlane_b32 s4, v242, 14
	v_readlane_b32 s5, v242, 15
	s_nop 1
	v_cndmask_b32_e64 v109, v99, 0, s[4:5]
	v_readlane_b32 s4, v242, 16
	v_readlane_b32 s5, v242, 17
	s_nop 1
	v_cndmask_b32_e64 v97, v98, 0, s[4:5]
	v_pk_add_f32 v[96:97], v[96:97], v[108:109]
	s_nop 0
	v_pk_fma_f32 v[108:109], v[30:31], v[96:97], v[114:115]

.LBB0_1610:
	s_andn2_b64 vcc, exec, s[96:97]
	s_cbranch_vccnz .LBB0_1612
	v_min_f32_e32 v103, 0, v109
	v_mul_f32_e32 v103, 0x3fb8aa3b, v103
	v_sub_f32_e32 v102, v100, v92
	v_exp_f32_e32 v104, v103
	v_sub_f32_e32 v103, v100, v93
	v_min_f32_e32 v102, 0, v102
	v_min_f32_e32 v103, 0, v103
	v_mul_f32_e32 v102, 0x3fb8aa3b, v102
	v_readlane_b32 s4, v242, 32
	v_mul_f32_e32 v103, 0x3fb8aa3b, v103
	v_exp_f32_e32 v102, v102
	v_readlane_b32 s5, v242, 33
	v_exp_f32_e32 v103, v103
	v_min_f32_e32 v105, 0, v108
	s_nop 0
	v_cndmask_b32_e64 v112, 0, v110, s[4:5]
	v_readlane_b32 s4, v242, 30
	v_readlane_b32 s5, v242, 31
	v_mul_f32_e32 v105, 0x3fb8aa3b, v105
	v_exp_f32_e32 v105, v105
	v_cndmask_b32_e64 v113, 0, v110, s[4:5]
	v_readlane_b32 s4, v242, 22
	v_pk_mul_f32 v[102:103], v[88:89], v[102:103]
	v_readlane_b32 s5, v242, 23
	s_waitcnt lgkmcnt(0)
	v_pk_mul_f32 v[96:97], v[96:97], v[104:105]
	v_cndmask_b32_e64 v103, v103, 0, s[4:5]
	v_readlane_b32 s4, v242, 24
	v_readlane_b32 s5, v242, 25
	s_nop 1
	v_cndmask_b32_e64 v102, v102, 0, s[4:5]
	v_readlane_b32 s4, v242, 26
	v_readlane_b32 s5, v242, 27
	s_nop 1
	v_cndmask_b32_e64 v97, v97, 0, s[4:5]
	v_readlane_b32 s4, v242, 28
	v_readlane_b32 s5, v242, 29
	s_nop 1
	v_cndmask_b32_e64 v96, v96, 0, s[4:5]
	v_pk_add_f32 v[96:97], v[102:103], v[96:97]
	v_sub_f32_e32 v102, v100, v94
	v_min_f32_e32 v102, 0, v102
	v_mul_f32_e32 v102, 0x3fb8aa3b, v102
	v_exp_f32_e32 v104, v102
	v_min_f32_e32 v102, 0, v107
	v_mul_f32_e32 v102, 0x3fb8aa3b, v102
	v_exp_f32_e32 v105, v102
	v_readlane_b32 s4, v242, 34
	v_pk_fma_f32 v[102:103], v[32:33], v[96:97], v[112:113]
	v_mul_f32_e32 v96, v90, v104
	v_readlane_b32 s5, v242, 35
	v_mul_f32_e32 v97, v98, v105
	v_mov_b32_e32 v98, v91
	v_cndmask_b32_e64 v96, v96, 0, s[4:5]
	v_readlane_b32 s4, v242, 36
	v_readlane_b32 s5, v242, 37
	s_nop 1
	v_cndmask_b32_e64 v104, v97, 0, s[4:5]
	v_sub_f32_e32 v97, v100, v95
	v_min_f32_e32 v97, 0, v97
	v_mul_f32_e32 v97, 0x3fb8aa3b, v97
	v_exp_f32_e32 v108, v97
	v_min_f32_e32 v97, 0, v106
	v_mul_f32_e32 v97, 0x3fb8aa3b, v97
	v_readlane_b32 s4, v242, 44
	v_exp_f32_e32 v109, v97
	v_readlane_b32 s5, v242, 45
	v_pk_mul_f32 v[98:99], v[98:99], v[108:109]
	s_nop 0
	v_cndmask_b32_e64 v106, 0, v110, s[4:5]
	v_readlane_b32 s4, v242, 42
	v_readlane_b32 s5, v242, 43
	s_nop 1
	v_cndmask_b32_e64 v107, 0, v110, s[4:5]
	v_readlane_b32 s4, v242, 38
	v_readlane_b32 s5, v242, 39
	s_nop 1
	v_cndmask_b32_e64 v105, v99, 0, s[4:5]
	v_readlane_b32 s4, v242, 40
	v_readlane_b32 s5, v242, 41
	s_nop 1
	v_cndmask_b32_e64 v97, v98, 0, s[4:5]
	v_pk_add_f32 v[96:97], v[96:97], v[104:105]
	s_nop 0
	v_pk_fma_f32 v[104:105], v[34:35], v[96:97], v[106:107]

.LBB0_1618:
	s_andn2_b64 vcc, exec, s[96:97]
	s_cbranch_vccnz .LBB0_1620
	v_min_f32_e32 v107, 0, v114
	v_mul_f32_e32 v107, 0x3fb8aa3b, v107
	v_sub_f32_e32 v106, v100, v92
	v_exp_f32_e32 v108, v107
	v_sub_f32_e32 v107, v100, v93
	v_min_f32_e32 v106, 0, v106
	v_min_f32_e32 v107, 0, v107
	v_mul_f32_e32 v106, 0x3fb8aa3b, v106
	v_readlane_b32 s4, v242, 56
	v_mul_f32_e32 v107, 0x3fb8aa3b, v107
	v_exp_f32_e32 v106, v106
	v_readlane_b32 s5, v242, 57
	v_exp_f32_e32 v107, v107
	v_min_f32_e32 v109, 0, v113
	s_nop 0
	v_cndmask_b32_e64 v114, 0, v110, s[4:5]
	v_readlane_b32 s4, v242, 54
	v_readlane_b32 s5, v242, 55
	v_mul_f32_e32 v109, 0x3fb8aa3b, v109
	v_exp_f32_e32 v109, v109
	v_cndmask_b32_e64 v115, 0, v110, s[4:5]
	v_readlane_b32 s4, v242, 46
	v_pk_mul_f32 v[106:107], v[88:89], v[106:107]
	v_readlane_b32 s5, v242, 47
	s_waitcnt lgkmcnt(0)
	v_pk_mul_f32 v[96:97], v[96:97], v[108:109]
	v_cndmask_b32_e64 v107, v107, 0, s[4:5]
	v_readlane_b32 s4, v242, 48
	v_readlane_b32 s5, v242, 49
	s_nop 1
	v_cndmask_b32_e64 v106, v106, 0, s[4:5]
	v_readlane_b32 s4, v242, 50
	v_readlane_b32 s5, v242, 51
	s_nop 1
	v_cndmask_b32_e64 v97, v97, 0, s[4:5]
	v_readlane_b32 s4, v242, 52
	v_readlane_b32 s5, v242, 53
	s_nop 1
	v_cndmask_b32_e64 v96, v96, 0, s[4:5]
	v_pk_add_f32 v[96:97], v[106:107], v[96:97]
	v_sub_f32_e32 v106, v100, v94
	v_min_f32_e32 v106, 0, v106
	v_mul_f32_e32 v106, 0x3fb8aa3b, v106
	v_exp_f32_e32 v108, v106
	v_min_f32_e32 v106, 0, v112
	v_mul_f32_e32 v106, 0x3fb8aa3b, v106
	v_exp_f32_e32 v109, v106
	v_readlane_b32 s4, v242, 58
	v_pk_fma_f32 v[106:107], v[36:37], v[96:97], v[114:115]
	v_mul_f32_e32 v96, v90, v108
	v_readlane_b32 s5, v242, 59
	v_mul_f32_e32 v97, v98, v109
	v_mov_b32_e32 v98, v91
	v_cndmask_b32_e64 v96, v96, 0, s[4:5]
	v_readlane_b32 s4, v242, 60
	v_readlane_b32 s5, v242, 61
	s_nop 1
	v_cndmask_b32_e64 v108, v97, 0, s[4:5]
	v_sub_f32_e32 v97, v100, v95
	v_min_f32_e32 v97, 0, v97
	v_mul_f32_e32 v97, 0x3fb8aa3b, v97
	v_exp_f32_e32 v112, v97
	v_min_f32_e32 v97, 0, v111
	v_mul_f32_e32 v97, 0x3fb8aa3b, v97
	v_readlane_b32 s4, v241, 4
	v_exp_f32_e32 v113, v97
	v_readlane_b32 s5, v241, 5
	v_pk_mul_f32 v[98:99], v[98:99], v[112:113]
	s_nop 0
	v_cndmask_b32_e64 v114, 0, v110, s[4:5]
	v_readlane_b32 s4, v241, 2
	v_readlane_b32 s5, v241, 3
	s_nop 1
	v_cndmask_b32_e64 v115, 0, v110, s[4:5]
	v_readlane_b32 s4, v242, 62
	v_readlane_b32 s5, v242, 63
	s_nop 1
	v_cndmask_b32_e64 v109, v99, 0, s[4:5]
	v_readlane_b32 s4, v241, 0
	v_readlane_b32 s5, v241, 1
	s_nop 1
	v_cndmask_b32_e64 v97, v98, 0, s[4:5]
	v_pk_add_f32 v[96:97], v[96:97], v[108:109]
	s_nop 0
	v_pk_fma_f32 v[108:109], v[38:39], v[96:97], v[114:115]

.LBB0_1626:
	s_andn2_b64 vcc, exec, s[96:97]
	s_cbranch_vccnz .LBB0_1628
	v_min_f32_e32 v103, 0, v109
	v_mul_f32_e32 v103, 0x3fb8aa3b, v103
	v_sub_f32_e32 v102, v100, v92
	v_exp_f32_e32 v104, v103
	v_sub_f32_e32 v103, v100, v93
	v_min_f32_e32 v102, 0, v102
	v_min_f32_e32 v103, 0, v103
	v_mul_f32_e32 v102, 0x3fb8aa3b, v102
	v_readlane_b32 s4, v241, 16
	v_mul_f32_e32 v103, 0x3fb8aa3b, v103
	v_exp_f32_e32 v102, v102
	v_readlane_b32 s5, v241, 17
	v_exp_f32_e32 v103, v103
	v_min_f32_e32 v105, 0, v108
	s_nop 0
	v_cndmask_b32_e64 v112, 0, v110, s[4:5]
	v_readlane_b32 s4, v241, 14
	v_readlane_b32 s5, v241, 15
	v_mul_f32_e32 v105, 0x3fb8aa3b, v105
	v_exp_f32_e32 v105, v105
	v_cndmask_b32_e64 v113, 0, v110, s[4:5]
	v_readlane_b32 s4, v241, 6
	v_pk_mul_f32 v[102:103], v[72:73], v[102:103]
	v_readlane_b32 s5, v241, 7
	s_waitcnt lgkmcnt(0)
	v_pk_mul_f32 v[96:97], v[96:97], v[104:105]
	v_cndmask_b32_e64 v103, v103, 0, s[4:5]
	v_readlane_b32 s4, v241, 8
	v_readlane_b32 s5, v241, 9
	s_nop 1
	v_cndmask_b32_e64 v102, v102, 0, s[4:5]
	v_readlane_b32 s4, v241, 10
	v_readlane_b32 s5, v241, 11
	s_nop 1
	v_cndmask_b32_e64 v97, v97, 0, s[4:5]
	v_readlane_b32 s4, v241, 12
	v_readlane_b32 s5, v241, 13
	s_nop 1
	v_cndmask_b32_e64 v96, v96, 0, s[4:5]
	v_pk_add_f32 v[96:97], v[102:103], v[96:97]
	v_sub_f32_e32 v102, v100, v94
	v_min_f32_e32 v102, 0, v102
	v_mul_f32_e32 v102, 0x3fb8aa3b, v102
	v_exp_f32_e32 v104, v102
	v_min_f32_e32 v102, 0, v107
	v_mul_f32_e32 v102, 0x3fb8aa3b, v102
	v_exp_f32_e32 v105, v102
	v_readlane_b32 s4, v241, 18
	v_pk_fma_f32 v[102:103], v[40:41], v[96:97], v[112:113]
	v_mul_f32_e32 v96, v74, v104
	v_readlane_b32 s5, v241, 19
	v_mul_f32_e32 v97, v98, v105
	v_mov_b32_e32 v98, v75
	v_cndmask_b32_e64 v96, v96, 0, s[4:5]
	v_readlane_b32 s4, v241, 20
	v_readlane_b32 s5, v241, 21
	s_nop 1
	v_cndmask_b32_e64 v104, v97, 0, s[4:5]
	v_sub_f32_e32 v97, v100, v95
	v_min_f32_e32 v97, 0, v97
	v_mul_f32_e32 v97, 0x3fb8aa3b, v97
	v_exp_f32_e32 v108, v97
	v_min_f32_e32 v97, 0, v106
	v_mul_f32_e32 v97, 0x3fb8aa3b, v97
	v_readlane_b32 s4, v241, 28
	v_exp_f32_e32 v109, v97
	v_readlane_b32 s5, v241, 29
	v_pk_mul_f32 v[98:99], v[98:99], v[108:109]
	s_nop 0
	v_cndmask_b32_e64 v106, 0, v110, s[4:5]
	v_readlane_b32 s4, v241, 26
	v_readlane_b32 s5, v241, 27
	s_nop 1
	v_cndmask_b32_e64 v107, 0, v110, s[4:5]
	v_readlane_b32 s4, v241, 22
	v_readlane_b32 s5, v241, 23
	s_nop 1
	v_cndmask_b32_e64 v105, v99, 0, s[4:5]
	v_readlane_b32 s4, v241, 24
	v_readlane_b32 s5, v241, 25
	s_nop 1
	v_cndmask_b32_e64 v97, v98, 0, s[4:5]
	v_pk_add_f32 v[96:97], v[96:97], v[104:105]
	s_nop 0
	v_pk_fma_f32 v[104:105], v[42:43], v[96:97], v[106:107]

.LBB0_1634:
	s_andn2_b64 vcc, exec, s[96:97]
	s_cbranch_vccnz .LBB0_1636
	v_min_f32_e32 v107, 0, v113
	v_mul_f32_e32 v107, 0x3fb8aa3b, v107
	v_sub_f32_e32 v106, v100, v92
	v_exp_f32_e32 v108, v107
	v_sub_f32_e32 v107, v100, v93
	v_min_f32_e32 v106, 0, v106
	v_min_f32_e32 v107, 0, v107
	v_mul_f32_e32 v106, 0x3fb8aa3b, v106
	v_mul_f32_e32 v107, 0x3fb8aa3b, v107
	v_exp_f32_e32 v106, v106
	v_exp_f32_e32 v107, v107
	v_min_f32_e32 v109, 0, v112
	v_readlane_b32 s4, v241, 34
	v_mul_f32_e32 v109, 0x3fb8aa3b, v109
	v_readlane_b32 s5, v241, 35
	v_exp_f32_e32 v109, v109
	v_pk_mul_f32 v[106:107], v[72:73], v[106:107]
	s_nop 0
	v_cndmask_b32_e64 v114, 0, v110, s[4:5]
	v_readlane_b32 s4, v241, 30
	v_readlane_b32 s5, v241, 31
	s_waitcnt lgkmcnt(0)
	v_pk_mul_f32 v[96:97], v[96:97], v[108:109]
	v_cndmask_b32_e64 v115, 0, v110, s[14:15]
	v_cndmask_b32_e64 v107, v107, 0, s[4:5]
	v_readlane_b32 s4, v241, 32
	v_readlane_b32 s5, v241, 33
	v_cndmask_b32_e64 v97, v97, 0, s[12:13]
	v_cndmask_b32_e64 v96, v96, 0, s[60:61]
	v_cndmask_b32_e64 v106, v106, 0, s[4:5]
	v_pk_add_f32 v[96:97], v[106:107], v[96:97]
	v_sub_f32_e32 v106, v100, v94
	v_min_f32_e32 v106, 0, v106
	v_mul_f32_e32 v106, 0x3fb8aa3b, v106
	v_exp_f32_e32 v108, v106
	v_min_f32_e32 v106, 0, v111
	v_mul_f32_e32 v106, 0x3fb8aa3b, v106
	v_exp_f32_e32 v109, v106
	v_readlane_b32 s4, v241, 36
	v_pk_fma_f32 v[106:107], v[44:45], v[96:97], v[114:115]
	v_mul_f32_e32 v96, v74, v108
	v_readlane_b32 s5, v241, 37
	v_mul_f32_e32 v97, v98, v109
	v_cndmask_b32_e64 v108, 0, v110, s[58:59]
	v_cndmask_b32_e64 v96, v96, 0, s[4:5]
	v_readlane_b32 s4, v241, 38
	v_readlane_b32 s5, v241, 39
	v_cndmask_b32_e64 v109, 0, v110, s[56:57]
	v_mov_b32_e32 v110, v99
	v_cndmask_b32_e64 v98, v97, 0, s[4:5]
	v_sub_f32_e32 v97, v100, v95
	v_min_f32_e32 v97, 0, v97
	v_mul_f32_e32 v97, 0x3fb8aa3b, v97
	v_exp_f32_e32 v113, v97
	v_min_f32_e32 v97, 0, v101
	v_mul_f32_e32 v97, 0x3fb8aa3b, v97
	v_exp_f32_e32 v112, v97
	v_mov_b32_e32 v111, v75
	v_readlane_b32 s4, v241, 42
	v_readlane_b32 s5, v241, 43
	v_pk_mul_f32 v[110:111], v[110:111], v[112:113]
	s_nop 0
	v_cndmask_b32_e64 v99, v110, 0, s[4:5]
	v_readlane_b32 s4, v241, 40
	v_readlane_b32 s5, v241, 41
	s_nop 1
	v_cndmask_b32_e64 v97, v111, 0, s[4:5]
	v_pk_add_f32 v[96:97], v[96:97], v[98:99]
	s_nop 0
	v_pk_fma_f32 v[108:109], v[46:47], v[96:97], v[108:109]

.LBB0_1947:
	v_readlane_b32 s4, v244, 47
	s_cmp_lt_i32 s4, 10
	s_cselect_b64 s[2:3], -1, 0
	s_and_b64 s[2:3], s[2:3], s[0:1]
	s_cmpk_lt_i32 s69, 0x600
	s_cselect_b64 s[0:1], -1, 0
	s_and_b64 s[0:1], s[2:3], s[0:1]
	s_andn2_b64 vcc, exec, s[0:1]
	v_readlane_b32 s5, v244, 48
	v_readlane_b32 s6, v244, 49
	v_readlane_b32 s7, v244, 50
	s_cbranch_vccnz .LBB0_1956
	v_and_b32_e32 v249, 63, v182
	v_readlane_b32 s4, v244, 6
	v_readlane_b32 s5, v244, 7
	v_readlane_b32 s6, v244, 39
	v_readlane_b32 s7, v244, 40
	v_readlane_b32 s8, v244, 41
	v_readlane_b32 s9, v244, 42
	v_lshlrev_b32_e32 v242, 2, v249
	s_nop 3
	global_load_dword v216, v242, s[6:7] offset:0
	global_load_dword v217, v242, s[6:7] offset:256
	global_load_dword v218, v242, s[6:7] offset:512
	global_load_dword v219, v242, s[6:7] offset:768
	global_load_dword v220, v242, s[8:9] offset:0
	global_load_dword v221, v242, s[8:9] offset:256
	global_load_dword v222, v242, s[8:9] offset:512
	global_load_dword v223, v242, s[8:9] offset:768
	v_and_b32_e32 v243, 15, v182
	v_bfe_u32 v245, v182, 4, 2
	v_lshl_or_b32 v246, s88, 4, v243
	v_lshlrev_b32_e32 v228, 11, v246
	v_lshl_add_u32 v238, v245, 3, v228
	v_lshl_add_u32 v228, v245, 4, v228
	v_add_u32_e32 v229, 0x40000, v228
	v_add_u32_e32 v239, 0x40000, v238
	v_lshlrev_b32_e32 v230, 4, v246
	v_mul_u32_u24_e32 v231, 528, v243
	v_lshl_add_u32 v232, v245, 3, v231
	v_lshl_add_u32 v231, v245, 4, v231
	v_lshrrev_b32_e32 v243, 5, v182
	v_and_b32_e32 v245, 31, v182
	v_lshlrev_b32_e32 v245, 4, v245
	v_lshl_add_u32 v224, v243, 11, v245
	v_mul_u32_u24_e32 v225, 5120, v243
	v_add_u32_e32 v225, v225, v245
	v_mul_u32_u24_e32 v226, 528, v243
	v_add_u32_e32 v226, v226, v245
	v_add_u32_e32 v227, 67584, v226
	v_and_b32_e32 v250, 3, v243
	v_bfe_u32 v242, v243, 2, 1
	v_lshl_or_b32 v250, v242, 4, v250
	v_bfe_u32 v242, v243, 3, 1
	v_lshl_or_b32 v250, v242, 2, v250
	v_mul_u32_u24_e32 v250, 528, v250
	v_add_u32_e32 v250, v250, v245
	v_add_u32_e32 v251, 67584, v250
	v_xor_b32_e32 v236, 16, v249
	v_lshlrev_b32_e32 v236, 2, v236
	v_xor_b32_e32 v237, 32, v249
	v_lshlrev_b32_e32 v237, 2, v237
	v_mov_b32_e32 v181, 0x358637bd
	s_waitcnt vmcnt(0)
	v_mul_f32_e32 v216, v216, v220
	v_mul_f32_e32 v217, v217, v221
	v_mul_f32_e32 v218, v218, v222
	v_mul_f32_e32 v219, v219, v223
	v_max_f32_e64 v216, |v216|, |v217|
	v_max_f32_e64 v218, |v218|, |v219|
	v_max_f32_e32 v216, v216, v218
	v_xor_b32_e32 v242, 1, v249
	v_lshlrev_b32_e32 v242, 2, v242
	ds_bpermute_b32 v243, v242, v216
	s_waitcnt lgkmcnt(0)
	v_max_f32_e32 v216, v216, v243
	v_xor_b32_e32 v242, 2, v249
	v_lshlrev_b32_e32 v242, 2, v242
	ds_bpermute_b32 v243, v242, v216
	s_waitcnt lgkmcnt(0)
	v_max_f32_e32 v216, v216, v243
	v_xor_b32_e32 v242, 4, v249
	v_lshlrev_b32_e32 v242, 2, v242
	ds_bpermute_b32 v243, v242, v216
	s_waitcnt lgkmcnt(0)
	v_max_f32_e32 v216, v216, v243
	v_xor_b32_e32 v242, 8, v249
	v_lshlrev_b32_e32 v242, 2, v242
	ds_bpermute_b32 v243, v242, v216
	s_waitcnt lgkmcnt(0)
	v_max_f32_e32 v216, v216, v243
	v_xor_b32_e32 v242, 16, v249
	v_lshlrev_b32_e32 v242, 2, v242
	ds_bpermute_b32 v243, v242, v216
	s_waitcnt lgkmcnt(0)
	v_max_f32_e32 v216, v216, v243
	v_xor_b32_e32 v242, 32, v249
	v_lshlrev_b32_e32 v242, 2, v242
	ds_bpermute_b32 v243, v242, v216
	s_waitcnt lgkmcnt(0)
	v_max_f32_e32 v216, v216, v243
	v_mul_f32_e32 v180, 0x41b8aa3b, v216
	s_lshr_b32 s0, s69, 6
	s_mul_i32 s0, s0, 0x5556
	s_lshr_b32 s0, s0, 16
	s_mul_i32 s1, s0, 192
	s_sub_i32 s1, s69, s1
	s_lshl_b32 s11, s1, 19
	s_lshl_b32 s12, s0, 9
	s_add_u32 s11, s11, s12
	s_add_u32 s12, s11, 0xf000000
	s_add_u32 s10, s4, s12
	s_addc_u32 s11, s5, 0
	s_lshl_b32 s12, s1, 12
	s_lshl_b32 s13, s0, 2
	s_add_u32 s12, s12, s13
	s_add_u32 s12, s12, 0x1fa60000
	s_add_u32 s12, s4, s12
	s_addc_u32 s13, s5, 0
	global_load_dwordx4 v[0:3], v228, s[10:11] offset:0
	global_load_dwordx4 v[4:7], v228, s[10:11] offset:64
	global_load_dwordx4 v[8:11], v228, s[10:11] offset:128
	global_load_dwordx4 v[12:15], v228, s[10:11] offset:192
	global_load_dwordx4 v[16:19], v228, s[10:11] offset:256
	global_load_dwordx4 v[20:23], v228, s[10:11] offset:320
	global_load_dwordx4 v[24:27], v228, s[10:11] offset:384
	global_load_dwordx4 v[28:31], v228, s[10:11] offset:448
	global_load_dwordx4 v[32:35], v229, s[10:11] offset:0
	global_load_dwordx4 v[36:39], v229, s[10:11] offset:64
	global_load_dwordx4 v[40:43], v229, s[10:11] offset:128
	global_load_dwordx4 v[44:47], v229, s[10:11] offset:192
	global_load_dwordx4 v[48:51], v229, s[10:11] offset:256
	global_load_dwordx4 v[52:55], v229, s[10:11] offset:320
	global_load_dwordx4 v[56:59], v229, s[10:11] offset:384
	global_load_dwordx4 v[60:63], v229, s[10:11] offset:448
	global_load_dword v247, v230, s[12:13]
	global_load_dword v248, v230, s[12:13] offset:2048
.Lxa_unit:
	s_lshr_b32 s0, s69, 6
	s_mul_i32 s0, s0, 0x5556
	s_lshr_b32 s0, s0, 16
	s_mul_i32 s1, s0, 192
	s_sub_i32 s1, s69, s1
	s_lshr_b32 s10, s1, 5
	s_sub_i32 s11, s1, 64
	s_lshr_b32 s11, s11, 4
	s_add_i32 s11, s11, 2
	s_cmp_lt_u32 s1, 64
	s_cselect_b32 s10, s10, s11
	s_lshl_b32 s11, s10, 19
	s_lshl_b32 s12, s0, 9
	s_add_u32 s11, s11, s12
	s_add_u32 s11, s11, 0x19000000
	s_add_u32 s6, s4, s11
	s_addc_u32 s7, s5, 0
	s_mul_i32 s11, s0, 0x140000
	s_lshl_b32 s12, s10, 9
	s_add_u32 s11, s11, s12
	s_add_u32 s11, s11, 0x19800000
	s_add_u32 s8, s4, s11
	s_addc_u32 s9, s5, 0
	s_lshl_b32 s12, s1, 19
	s_lshl_b32 s13, s0, 9
	s_add_u32 s12, s12, s13
	s_add_u32 s12, s12, 0x9000000
	s_add_u32 s14, s4, s12
	s_addc_u32 s15, s5, 0
	global_load_dwordx4 v[128:131], v224, s[6:7]
	s_add_u32 s6, s6, 0x8000
	s_addc_u32 s7, s7, 0
	global_load_dwordx4 v[132:135], v224, s[6:7]
	s_add_u32 s6, s6, 0x8000
	s_addc_u32 s7, s7, 0
	global_load_dwordx4 v[136:139], v224, s[6:7]
	s_add_u32 s6, s6, 0x8000
	s_addc_u32 s7, s7, 0
	global_load_dwordx4 v[140:143], v224, s[6:7]
	s_add_u32 s6, s6, 0x8000
	s_addc_u32 s7, s7, 0
	global_load_dwordx4 v[144:147], v224, s[6:7]
	s_add_u32 s6, s6, 0x8000
	s_addc_u32 s7, s7, 0
	global_load_dwordx4 v[148:151], v224, s[6:7]
	s_add_u32 s6, s6, 0x8000
	s_addc_u32 s7, s7, 0
	global_load_dwordx4 v[152:155], v224, s[6:7]
	s_add_u32 s6, s6, 0x8000
	s_addc_u32 s7, s7, 0
	global_load_dwordx4 v[156:159], v224, s[6:7]
	s_add_u32 s6, s6, 0x8000
	s_addc_u32 s7, s7, 0
	global_load_dwordx4 v[184:187], v224, s[6:7]
	s_add_u32 s6, s6, 0x8000
	s_addc_u32 s7, s7, 0
	global_load_dwordx4 v[188:191], v224, s[6:7]
	s_add_u32 s6, s6, 0x8000
	s_addc_u32 s7, s7, 0
	global_load_dwordx4 v[192:195], v224, s[6:7]
	s_add_u32 s6, s6, 0x8000
	s_addc_u32 s7, s7, 0
	global_load_dwordx4 v[196:199], v224, s[6:7]
	s_add_u32 s6, s6, 0x8000
	s_addc_u32 s7, s7, 0
	global_load_dwordx4 v[200:203], v224, s[6:7]
	s_add_u32 s6, s6, 0x8000
	s_addc_u32 s7, s7, 0
	global_load_dwordx4 v[204:207], v224, s[6:7]
	s_add_u32 s6, s6, 0x8000
	s_addc_u32 s7, s7, 0
	global_load_dwordx4 v[208:211], v224, s[6:7]
	s_add_u32 s6, s6, 0x8000
	s_addc_u32 s7, s7, 0
	global_load_dwordx4 v[212:215], v224, s[6:7]
	s_waitcnt vmcnt(12)
	ds_write_b128 v226, v[128:131] offset:0
	ds_write_b128 v226, v[132:135] offset:8448
	ds_write_b128 v226, v[136:139] offset:16896
	ds_write_b128 v226, v[140:143] offset:25344
	s_waitcnt vmcnt(8)
	ds_write_b128 v226, v[144:147] offset:33792
	ds_write_b128 v226, v[148:151] offset:42240
	ds_write_b128 v226, v[152:155] offset:50688
	ds_write_b128 v226, v[156:159] offset:59136
	s_waitcnt vmcnt(4)
	ds_write_b128 v227, v[184:187] offset:0
	ds_write_b128 v227, v[188:191] offset:8448
	ds_write_b128 v227, v[192:195] offset:16896
	ds_write_b128 v227, v[196:199] offset:25344
	s_waitcnt vmcnt(0)
	ds_write_b128 v227, v[200:203] offset:33792
	ds_write_b128 v227, v[204:207] offset:42240
	ds_write_b128 v227, v[208:211] offset:50688
	ds_write_b128 v227, v[212:215] offset:59136
	s_waitcnt vmcnt(0)
	v_fmamk_f32 v178, v247, 0x3b800000, v181
	v_fmamk_f32 v179, v248, 0x3b800000, v181
	v_rsq_f32_e32 v178, v178
	v_rsq_f32_e32 v179, v179
	v_mov_b32_e32 v176, 0
	v_mov_b32_e32 v177, 0
	v_mul_f32_e32 v178, 0x3db8aa3b, v178
	v_mul_f32_e32 v179, 0x3db8aa3b, v179
	s_waitcnt lgkmcnt(0)
	s_barrier
	v_mov_b32_e32 v233, v231
	ds_read_b128 v[128:131], v233 offset:0
	ds_read_b128 v[132:135], v233 offset:64
	ds_read_b128 v[136:139], v233 offset:128
	ds_read_b128 v[140:143], v233 offset:192
	ds_read_b128 v[144:147], v233 offset:256
	ds_read_b128 v[148:151], v233 offset:320
	ds_read_b128 v[152:155], v233 offset:384
	ds_read_b128 v[156:159], v233 offset:448
	s_waitcnt lgkmcnt(0)
	ds_read_b128 v[184:187], v233 offset:8448
	ds_read_b128 v[188:191], v233 offset:8512
	ds_read_b128 v[192:195], v233 offset:8576
	ds_read_b128 v[196:199], v233 offset:8640
	ds_read_b128 v[200:203], v233 offset:8704
	ds_read_b128 v[204:207], v233 offset:8768
	ds_read_b128 v[208:211], v233 offset:8832
	ds_read_b128 v[212:215], v233 offset:8896
	v_mfma_f32_16x16x32_bf16 v[160:163], v[128:131], v[0:3], 0
	v_mfma_f32_16x16x32_bf16 v[164:167], v[128:131], v[32:35], 0
	v_mfma_f32_16x16x32_bf16 v[160:163], v[132:135], v[4:7], v[160:163]
	v_mfma_f32_16x16x32_bf16 v[164:167], v[132:135], v[36:39], v[164:167]
	v_mfma_f32_16x16x32_bf16 v[160:163], v[136:139], v[8:11], v[160:163]
	v_mfma_f32_16x16x32_bf16 v[164:167], v[136:139], v[40:43], v[164:167]
	v_mfma_f32_16x16x32_bf16 v[160:163], v[140:143], v[12:15], v[160:163]
	v_mfma_f32_16x16x32_bf16 v[164:167], v[140:143], v[44:47], v[164:167]
	v_mfma_f32_16x16x32_bf16 v[160:163], v[144:147], v[16:19], v[160:163]
	v_mfma_f32_16x16x32_bf16 v[164:167], v[144:147], v[48:51], v[164:167]
	v_mfma_f32_16x16x32_bf16 v[160:163], v[148:151], v[20:23], v[160:163]
	v_mfma_f32_16x16x32_bf16 v[164:167], v[148:151], v[52:55], v[164:167]
	v_mfma_f32_16x16x32_bf16 v[160:163], v[152:155], v[24:27], v[160:163]
	v_mfma_f32_16x16x32_bf16 v[164:167], v[152:155], v[56:59], v[164:167]
	v_mfma_f32_16x16x32_bf16 v[160:163], v[156:159], v[28:31], v[160:163]
	v_mfma_f32_16x16x32_bf16 v[164:167], v[156:159], v[60:63], v[164:167]
	s_waitcnt lgkmcnt(0)
	ds_read_b128 v[128:131], v233 offset:16896
	ds_read_b128 v[132:135], v233 offset:16960
	ds_read_b128 v[136:139], v233 offset:17024
	ds_read_b128 v[140:143], v233 offset:17088
	ds_read_b128 v[144:147], v233 offset:17152
	ds_read_b128 v[148:151], v233 offset:17216
	ds_read_b128 v[152:155], v233 offset:17280
	ds_read_b128 v[156:159], v233 offset:17344
	v_mfma_f32_16x16x32_bf16 v[168:171], v[184:187], v[0:3], 0
	v_fma_f32 v216, v160, v178, -v180
	v_fma_f32 v217, v161, v178, -v180
	v_mfma_f32_16x16x32_bf16 v[172:175], v[184:187], v[32:35], 0
	v_fma_f32 v218, v162, v178, -v180
	v_fma_f32 v219, v163, v178, -v180
	v_mfma_f32_16x16x32_bf16 v[168:171], v[188:191], v[4:7], v[168:171]
	v_exp_f32_e32 v216, v216
	v_exp_f32_e32 v217, v217
	v_mfma_f32_16x16x32_bf16 v[172:175], v[188:191], v[36:39], v[172:175]
	v_exp_f32_e32 v218, v218
	v_exp_f32_e32 v219, v219
	v_mfma_f32_16x16x32_bf16 v[168:171], v[192:195], v[8:11], v[168:171]
	v_fma_f32 v220, v164, v179, -v180
	v_fma_f32 v221, v165, v179, -v180
	v_mfma_f32_16x16x32_bf16 v[172:175], v[192:195], v[40:43], v[172:175]
	v_fma_f32 v222, v166, v179, -v180
	v_fma_f32 v223, v167, v179, -v180
	v_mfma_f32_16x16x32_bf16 v[168:171], v[196:199], v[12:15], v[168:171]
	v_exp_f32_e32 v220, v220
	v_exp_f32_e32 v221, v221
	v_mfma_f32_16x16x32_bf16 v[172:175], v[196:199], v[44:47], v[172:175]
	v_exp_f32_e32 v222, v222
	v_exp_f32_e32 v223, v223
	v_mfma_f32_16x16x32_bf16 v[168:171], v[200:203], v[16:19], v[168:171]
	v_add_f32_e32 v176, v176, v216
	v_add_f32_e32 v176, v176, v217
	v_mfma_f32_16x16x32_bf16 v[172:175], v[200:203], v[48:51], v[172:175]
	v_cvt_pk_bf16_f32 v64, v216, v217
	v_add_f32_e32 v176, v176, v218
	v_mfma_f32_16x16x32_bf16 v[168:171], v[204:207], v[20:23], v[168:171]
	v_add_f32_e32 v176, v176, v219
	v_cvt_pk_bf16_f32 v65, v218, v219
	v_mfma_f32_16x16x32_bf16 v[172:175], v[204:207], v[52:55], v[172:175]
	v_add_f32_e32 v177, v177, v220
	v_add_f32_e32 v177, v177, v221
	v_mfma_f32_16x16x32_bf16 v[168:171], v[208:211], v[24:27], v[168:171]
	v_cvt_pk_bf16_f32 v96, v220, v221
	v_add_f32_e32 v177, v177, v222
	v_mfma_f32_16x16x32_bf16 v[172:175], v[208:211], v[56:59], v[172:175]
	v_add_f32_e32 v177, v177, v223
	v_cvt_pk_bf16_f32 v97, v222, v223
	v_mfma_f32_16x16x32_bf16 v[168:171], v[212:215], v[28:31], v[168:171]
	v_mfma_f32_16x16x32_bf16 v[172:175], v[212:215], v[60:63], v[172:175]
	s_waitcnt lgkmcnt(0)
	ds_read_b128 v[184:187], v233 offset:25344
	ds_read_b128 v[188:191], v233 offset:25408
	ds_read_b128 v[192:195], v233 offset:25472
	ds_read_b128 v[196:199], v233 offset:25536
	ds_read_b128 v[200:203], v233 offset:25600
	ds_read_b128 v[204:207], v233 offset:25664
	ds_read_b128 v[208:211], v233 offset:25728
	ds_read_b128 v[212:215], v233 offset:25792
	v_mfma_f32_16x16x32_bf16 v[160:163], v[128:131], v[0:3], 0
	v_fma_f32 v216, v168, v178, -v180
	v_fma_f32 v217, v169, v178, -v180
	v_mfma_f32_16x16x32_bf16 v[164:167], v[128:131], v[32:35], 0
	v_fma_f32 v218, v170, v178, -v180
	v_fma_f32 v219, v171, v178, -v180
	v_mfma_f32_16x16x32_bf16 v[160:163], v[132:135], v[4:7], v[160:163]
	v_exp_f32_e32 v216, v216
	v_exp_f32_e32 v217, v217
	v_mfma_f32_16x16x32_bf16 v[164:167], v[132:135], v[36:39], v[164:167]
	v_exp_f32_e32 v218, v218
	v_exp_f32_e32 v219, v219
	v_mfma_f32_16x16x32_bf16 v[160:163], v[136:139], v[8:11], v[160:163]
	v_fma_f32 v220, v172, v179, -v180
	v_fma_f32 v221, v173, v179, -v180
	v_mfma_f32_16x16x32_bf16 v[164:167], v[136:139], v[40:43], v[164:167]
	v_fma_f32 v222, v174, v179, -v180
	v_fma_f32 v223, v175, v179, -v180
	v_mfma_f32_16x16x32_bf16 v[160:163], v[140:143], v[12:15], v[160:163]
	v_exp_f32_e32 v220, v220
	v_exp_f32_e32 v221, v221
	v_mfma_f32_16x16x32_bf16 v[164:167], v[140:143], v[44:47], v[164:167]
	v_exp_f32_e32 v222, v222
	v_exp_f32_e32 v223, v223
	v_mfma_f32_16x16x32_bf16 v[160:163], v[144:147], v[16:19], v[160:163]
	v_add_f32_e32 v176, v176, v216
	v_add_f32_e32 v176, v176, v217
	v_mfma_f32_16x16x32_bf16 v[164:167], v[144:147], v[48:51], v[164:167]
	v_cvt_pk_bf16_f32 v66, v216, v217
	v_add_f32_e32 v176, v176, v218
	v_mfma_f32_16x16x32_bf16 v[160:163], v[148:151], v[20:23], v[160:163]
	v_add_f32_e32 v176, v176, v219
	v_cvt_pk_bf16_f32 v67, v218, v219
	v_mfma_f32_16x16x32_bf16 v[164:167], v[148:151], v[52:55], v[164:167]
	v_add_f32_e32 v177, v177, v220
	v_add_f32_e32 v177, v177, v221
	v_mfma_f32_16x16x32_bf16 v[160:163], v[152:155], v[24:27], v[160:163]
	v_cvt_pk_bf16_f32 v98, v220, v221
	v_add_f32_e32 v177, v177, v222
	v_mfma_f32_16x16x32_bf16 v[164:167], v[152:155], v[56:59], v[164:167]
	v_add_f32_e32 v177, v177, v223
	v_cvt_pk_bf16_f32 v99, v222, v223
	v_mfma_f32_16x16x32_bf16 v[160:163], v[156:159], v[28:31], v[160:163]
	v_mfma_f32_16x16x32_bf16 v[164:167], v[156:159], v[60:63], v[164:167]
	s_waitcnt lgkmcnt(0)
	ds_read_b128 v[128:131], v233 offset:33792
	ds_read_b128 v[132:135], v233 offset:33856
	ds_read_b128 v[136:139], v233 offset:33920
	ds_read_b128 v[140:143], v233 offset:33984
	ds_read_b128 v[144:147], v233 offset:34048
	ds_read_b128 v[148:151], v233 offset:34112
	ds_read_b128 v[152:155], v233 offset:34176
	ds_read_b128 v[156:159], v233 offset:34240
	v_mfma_f32_16x16x32_bf16 v[168:171], v[184:187], v[0:3], 0
	v_fma_f32 v216, v160, v178, -v180
	v_fma_f32 v217, v161, v178, -v180
	v_mfma_f32_16x16x32_bf16 v[172:175], v[184:187], v[32:35], 0
	v_fma_f32 v218, v162, v178, -v180
	v_fma_f32 v219, v163, v178, -v180
	v_mfma_f32_16x16x32_bf16 v[168:171], v[188:191], v[4:7], v[168:171]
	v_exp_f32_e32 v216, v216
	v_exp_f32_e32 v217, v217
	v_mfma_f32_16x16x32_bf16 v[172:175], v[188:191], v[36:39], v[172:175]
	v_exp_f32_e32 v218, v218
	v_exp_f32_e32 v219, v219
	v_mfma_f32_16x16x32_bf16 v[168:171], v[192:195], v[8:11], v[168:171]
	v_fma_f32 v220, v164, v179, -v180
	v_fma_f32 v221, v165, v179, -v180
	v_mfma_f32_16x16x32_bf16 v[172:175], v[192:195], v[40:43], v[172:175]
	v_fma_f32 v222, v166, v179, -v180
	v_fma_f32 v223, v167, v179, -v180
	v_mfma_f32_16x16x32_bf16 v[168:171], v[196:199], v[12:15], v[168:171]
	v_exp_f32_e32 v220, v220
	v_exp_f32_e32 v221, v221
	v_mfma_f32_16x16x32_bf16 v[172:175], v[196:199], v[44:47], v[172:175]
	v_exp_f32_e32 v222, v222
	v_exp_f32_e32 v223, v223
	v_mfma_f32_16x16x32_bf16 v[168:171], v[200:203], v[16:19], v[168:171]
	v_add_f32_e32 v176, v176, v216
	v_add_f32_e32 v176, v176, v217
	v_mfma_f32_16x16x32_bf16 v[172:175], v[200:203], v[48:51], v[172:175]
	v_cvt_pk_bf16_f32 v68, v216, v217
	v_add_f32_e32 v176, v176, v218
	v_mfma_f32_16x16x32_bf16 v[168:171], v[204:207], v[20:23], v[168:171]
	v_add_f32_e32 v176, v176, v219
	v_cvt_pk_bf16_f32 v69, v218, v219
	v_mfma_f32_16x16x32_bf16 v[172:175], v[204:207], v[52:55], v[172:175]
	v_add_f32_e32 v177, v177, v220
	v_add_f32_e32 v177, v177, v221
	v_mfma_f32_16x16x32_bf16 v[168:171], v[208:211], v[24:27], v[168:171]
	v_cvt_pk_bf16_f32 v100, v220, v221
	v_add_f32_e32 v177, v177, v222
	v_mfma_f32_16x16x32_bf16 v[172:175], v[208:211], v[56:59], v[172:175]
	v_add_f32_e32 v177, v177, v223
	v_cvt_pk_bf16_f32 v101, v222, v223
	v_mfma_f32_16x16x32_bf16 v[168:171], v[212:215], v[28:31], v[168:171]
	v_mfma_f32_16x16x32_bf16 v[172:175], v[212:215], v[60:63], v[172:175]
	s_waitcnt lgkmcnt(0)
	ds_read_b128 v[184:187], v233 offset:42240
	ds_read_b128 v[188:191], v233 offset:42304
	ds_read_b128 v[192:195], v233 offset:42368
	ds_read_b128 v[196:199], v233 offset:42432
	ds_read_b128 v[200:203], v233 offset:42496
	ds_read_b128 v[204:207], v233 offset:42560
	ds_read_b128 v[208:211], v233 offset:42624
	ds_read_b128 v[212:215], v233 offset:42688
	v_mfma_f32_16x16x32_bf16 v[160:163], v[128:131], v[0:3], 0
	v_fma_f32 v216, v168, v178, -v180
	v_fma_f32 v217, v169, v178, -v180
	v_mfma_f32_16x16x32_bf16 v[164:167], v[128:131], v[32:35], 0
	v_fma_f32 v218, v170, v178, -v180
	v_fma_f32 v219, v171, v178, -v180
	v_mfma_f32_16x16x32_bf16 v[160:163], v[132:135], v[4:7], v[160:163]
	v_exp_f32_e32 v216, v216
	v_exp_f32_e32 v217, v217
	v_mfma_f32_16x16x32_bf16 v[164:167], v[132:135], v[36:39], v[164:167]
	v_exp_f32_e32 v218, v218
	v_exp_f32_e32 v219, v219
	v_mfma_f32_16x16x32_bf16 v[160:163], v[136:139], v[8:11], v[160:163]
	v_fma_f32 v220, v172, v179, -v180
	v_fma_f32 v221, v173, v179, -v180
	v_mfma_f32_16x16x32_bf16 v[164:167], v[136:139], v[40:43], v[164:167]
	v_fma_f32 v222, v174, v179, -v180
	v_fma_f32 v223, v175, v179, -v180
	v_mfma_f32_16x16x32_bf16 v[160:163], v[140:143], v[12:15], v[160:163]
	v_exp_f32_e32 v220, v220
	v_exp_f32_e32 v221, v221
	v_mfma_f32_16x16x32_bf16 v[164:167], v[140:143], v[44:47], v[164:167]
	v_exp_f32_e32 v222, v222
	v_exp_f32_e32 v223, v223
	v_mfma_f32_16x16x32_bf16 v[160:163], v[144:147], v[16:19], v[160:163]
	v_add_f32_e32 v176, v176, v216
	v_add_f32_e32 v176, v176, v217
	v_mfma_f32_16x16x32_bf16 v[164:167], v[144:147], v[48:51], v[164:167]
	v_cvt_pk_bf16_f32 v70, v216, v217
	v_add_f32_e32 v176, v176, v218
	v_mfma_f32_16x16x32_bf16 v[160:163], v[148:151], v[20:23], v[160:163]
	v_add_f32_e32 v176, v176, v219
	v_cvt_pk_bf16_f32 v71, v218, v219
	v_mfma_f32_16x16x32_bf16 v[164:167], v[148:151], v[52:55], v[164:167]
	v_add_f32_e32 v177, v177, v220
	v_add_f32_e32 v177, v177, v221
	v_mfma_f32_16x16x32_bf16 v[160:163], v[152:155], v[24:27], v[160:163]
	v_cvt_pk_bf16_f32 v102, v220, v221
	v_add_f32_e32 v177, v177, v222
	v_mfma_f32_16x16x32_bf16 v[164:167], v[152:155], v[56:59], v[164:167]
	v_add_f32_e32 v177, v177, v223
	v_cvt_pk_bf16_f32 v103, v222, v223
	v_mfma_f32_16x16x32_bf16 v[160:163], v[156:159], v[28:31], v[160:163]
	v_mfma_f32_16x16x32_bf16 v[164:167], v[156:159], v[60:63], v[164:167]
	s_waitcnt lgkmcnt(0)
	ds_read_b128 v[128:131], v233 offset:50688
	ds_read_b128 v[132:135], v233 offset:50752
	ds_read_b128 v[136:139], v233 offset:50816
	ds_read_b128 v[140:143], v233 offset:50880
	ds_read_b128 v[144:147], v233 offset:50944
	ds_read_b128 v[148:151], v233 offset:51008
	ds_read_b128 v[152:155], v233 offset:51072
	ds_read_b128 v[156:159], v233 offset:51136
	v_mfma_f32_16x16x32_bf16 v[168:171], v[184:187], v[0:3], 0
	v_fma_f32 v216, v160, v178, -v180
	v_fma_f32 v217, v161, v178, -v180
	v_mfma_f32_16x16x32_bf16 v[172:175], v[184:187], v[32:35], 0
	v_fma_f32 v218, v162, v178, -v180
	v_fma_f32 v219, v163, v178, -v180
	v_mfma_f32_16x16x32_bf16 v[168:171], v[188:191], v[4:7], v[168:171]
	v_exp_f32_e32 v216, v216
	v_exp_f32_e32 v217, v217
	v_mfma_f32_16x16x32_bf16 v[172:175], v[188:191], v[36:39], v[172:175]
	v_exp_f32_e32 v218, v218
	v_exp_f32_e32 v219, v219
	v_mfma_f32_16x16x32_bf16 v[168:171], v[192:195], v[8:11], v[168:171]
	v_fma_f32 v220, v164, v179, -v180
	v_fma_f32 v221, v165, v179, -v180
	v_mfma_f32_16x16x32_bf16 v[172:175], v[192:195], v[40:43], v[172:175]
	v_fma_f32 v222, v166, v179, -v180
	v_fma_f32 v223, v167, v179, -v180
	v_mfma_f32_16x16x32_bf16 v[168:171], v[196:199], v[12:15], v[168:171]
	v_exp_f32_e32 v220, v220
	v_exp_f32_e32 v221, v221
	v_mfma_f32_16x16x32_bf16 v[172:175], v[196:199], v[44:47], v[172:175]
	v_exp_f32_e32 v222, v222
	v_exp_f32_e32 v223, v223
	v_mfma_f32_16x16x32_bf16 v[168:171], v[200:203], v[16:19], v[168:171]
	v_add_f32_e32 v176, v176, v216
	v_add_f32_e32 v176, v176, v217
	v_mfma_f32_16x16x32_bf16 v[172:175], v[200:203], v[48:51], v[172:175]
	v_cvt_pk_bf16_f32 v72, v216, v217
	v_add_f32_e32 v176, v176, v218
	v_mfma_f32_16x16x32_bf16 v[168:171], v[204:207], v[20:23], v[168:171]
	v_add_f32_e32 v176, v176, v219
	v_cvt_pk_bf16_f32 v73, v218, v219
	v_mfma_f32_16x16x32_bf16 v[172:175], v[204:207], v[52:55], v[172:175]
	v_add_f32_e32 v177, v177, v220
	v_add_f32_e32 v177, v177, v221
	v_mfma_f32_16x16x32_bf16 v[168:171], v[208:211], v[24:27], v[168:171]
	v_cvt_pk_bf16_f32 v104, v220, v221
	v_add_f32_e32 v177, v177, v222
	v_mfma_f32_16x16x32_bf16 v[172:175], v[208:211], v[56:59], v[172:175]
	v_add_f32_e32 v177, v177, v223
	v_cvt_pk_bf16_f32 v105, v222, v223
	v_mfma_f32_16x16x32_bf16 v[168:171], v[212:215], v[28:31], v[168:171]
	v_mfma_f32_16x16x32_bf16 v[172:175], v[212:215], v[60:63], v[172:175]
	s_waitcnt lgkmcnt(0)
	v_add_u32_e32 v233, 59136, v233
	ds_read_b128 v[184:187], v233 offset:0
	ds_read_b128 v[188:191], v233 offset:64
	ds_read_b128 v[192:195], v233 offset:128
	ds_read_b128 v[196:199], v233 offset:192
	ds_read_b128 v[200:203], v233 offset:256
	ds_read_b128 v[204:207], v233 offset:320
	ds_read_b128 v[208:211], v233 offset:384
	ds_read_b128 v[212:215], v233 offset:448
	v_mfma_f32_16x16x32_bf16 v[160:163], v[128:131], v[0:3], 0
	v_fma_f32 v216, v168, v178, -v180
	v_fma_f32 v217, v169, v178, -v180
	v_mfma_f32_16x16x32_bf16 v[164:167], v[128:131], v[32:35], 0
	v_fma_f32 v218, v170, v178, -v180
	v_fma_f32 v219, v171, v178, -v180
	v_mfma_f32_16x16x32_bf16 v[160:163], v[132:135], v[4:7], v[160:163]
	v_exp_f32_e32 v216, v216
	v_exp_f32_e32 v217, v217
	v_mfma_f32_16x16x32_bf16 v[164:167], v[132:135], v[36:39], v[164:167]
	v_exp_f32_e32 v218, v218
	v_exp_f32_e32 v219, v219
	v_mfma_f32_16x16x32_bf16 v[160:163], v[136:139], v[8:11], v[160:163]
	v_fma_f32 v220, v172, v179, -v180
	v_fma_f32 v221, v173, v179, -v180
	v_mfma_f32_16x16x32_bf16 v[164:167], v[136:139], v[40:43], v[164:167]
	v_fma_f32 v222, v174, v179, -v180
	v_fma_f32 v223, v175, v179, -v180
	v_mfma_f32_16x16x32_bf16 v[160:163], v[140:143], v[12:15], v[160:163]
	v_exp_f32_e32 v220, v220
	v_exp_f32_e32 v221, v221
	v_mfma_f32_16x16x32_bf16 v[164:167], v[140:143], v[44:47], v[164:167]
	v_exp_f32_e32 v222, v222
	v_exp_f32_e32 v223, v223
	v_mfma_f32_16x16x32_bf16 v[160:163], v[144:147], v[16:19], v[160:163]
	v_add_f32_e32 v176, v176, v216
	v_add_f32_e32 v176, v176, v217
	v_mfma_f32_16x16x32_bf16 v[164:167], v[144:147], v[48:51], v[164:167]
	v_cvt_pk_bf16_f32 v74, v216, v217
	v_add_f32_e32 v176, v176, v218
	v_mfma_f32_16x16x32_bf16 v[160:163], v[148:151], v[20:23], v[160:163]
	v_add_f32_e32 v176, v176, v219
	v_cvt_pk_bf16_f32 v75, v218, v219
	v_mfma_f32_16x16x32_bf16 v[164:167], v[148:151], v[52:55], v[164:167]
	v_add_f32_e32 v177, v177, v220
	v_add_f32_e32 v177, v177, v221
	v_mfma_f32_16x16x32_bf16 v[160:163], v[152:155], v[24:27], v[160:163]
	v_cvt_pk_bf16_f32 v106, v220, v221
	v_add_f32_e32 v177, v177, v222
	v_mfma_f32_16x16x32_bf16 v[164:167], v[152:155], v[56:59], v[164:167]
	v_add_f32_e32 v177, v177, v223
	v_cvt_pk_bf16_f32 v107, v222, v223
	v_mfma_f32_16x16x32_bf16 v[160:163], v[156:159], v[28:31], v[160:163]
	v_mfma_f32_16x16x32_bf16 v[164:167], v[156:159], v[60:63], v[164:167]
	s_waitcnt lgkmcnt(0)
	ds_read_b128 v[128:131], v233 offset:8448
	ds_read_b128 v[132:135], v233 offset:8512
	ds_read_b128 v[136:139], v233 offset:8576
	ds_read_b128 v[140:143], v233 offset:8640
	ds_read_b128 v[144:147], v233 offset:8704
	ds_read_b128 v[148:151], v233 offset:8768
	ds_read_b128 v[152:155], v233 offset:8832
	ds_read_b128 v[156:159], v233 offset:8896
	v_mfma_f32_16x16x32_bf16 v[168:171], v[184:187], v[0:3], 0
	v_fma_f32 v216, v160, v178, -v180
	v_fma_f32 v217, v161, v178, -v180
	v_mfma_f32_16x16x32_bf16 v[172:175], v[184:187], v[32:35], 0
	v_fma_f32 v218, v162, v178, -v180
	v_fma_f32 v219, v163, v178, -v180
	v_mfma_f32_16x16x32_bf16 v[168:171], v[188:191], v[4:7], v[168:171]
	v_exp_f32_e32 v216, v216
	v_exp_f32_e32 v217, v217
	v_mfma_f32_16x16x32_bf16 v[172:175], v[188:191], v[36:39], v[172:175]
	v_exp_f32_e32 v218, v218
	v_exp_f32_e32 v219, v219
	v_mfma_f32_16x16x32_bf16 v[168:171], v[192:195], v[8:11], v[168:171]
	v_fma_f32 v220, v164, v179, -v180
	v_fma_f32 v221, v165, v179, -v180
	v_mfma_f32_16x16x32_bf16 v[172:175], v[192:195], v[40:43], v[172:175]
	v_fma_f32 v222, v166, v179, -v180
	v_fma_f32 v223, v167, v179, -v180
	v_mfma_f32_16x16x32_bf16 v[168:171], v[196:199], v[12:15], v[168:171]
	v_exp_f32_e32 v220, v220
	v_exp_f32_e32 v221, v221
	v_mfma_f32_16x16x32_bf16 v[172:175], v[196:199], v[44:47], v[172:175]
	v_exp_f32_e32 v222, v222
	v_exp_f32_e32 v223, v223
	v_mfma_f32_16x16x32_bf16 v[168:171], v[200:203], v[16:19], v[168:171]
	v_add_f32_e32 v176, v176, v216
	v_add_f32_e32 v176, v176, v217
	v_mfma_f32_16x16x32_bf16 v[172:175], v[200:203], v[48:51], v[172:175]
	v_cvt_pk_bf16_f32 v76, v216, v217
	v_add_f32_e32 v176, v176, v218
	v_mfma_f32_16x16x32_bf16 v[168:171], v[204:207], v[20:23], v[168:171]
	v_add_f32_e32 v176, v176, v219
	v_cvt_pk_bf16_f32 v77, v218, v219
	v_mfma_f32_16x16x32_bf16 v[172:175], v[204:207], v[52:55], v[172:175]
	v_add_f32_e32 v177, v177, v220
	v_add_f32_e32 v177, v177, v221
	v_mfma_f32_16x16x32_bf16 v[168:171], v[208:211], v[24:27], v[168:171]
	v_cvt_pk_bf16_f32 v108, v220, v221
	v_add_f32_e32 v177, v177, v222
	v_mfma_f32_16x16x32_bf16 v[172:175], v[208:211], v[56:59], v[172:175]
	v_add_f32_e32 v177, v177, v223
	v_cvt_pk_bf16_f32 v109, v222, v223
	v_mfma_f32_16x16x32_bf16 v[168:171], v[212:215], v[28:31], v[168:171]
	v_mfma_f32_16x16x32_bf16 v[172:175], v[212:215], v[60:63], v[172:175]
	s_waitcnt lgkmcnt(0)
	ds_read_b128 v[184:187], v233 offset:16896
	ds_read_b128 v[188:191], v233 offset:16960
	ds_read_b128 v[192:195], v233 offset:17024
	ds_read_b128 v[196:199], v233 offset:17088
	ds_read_b128 v[200:203], v233 offset:17152
	ds_read_b128 v[204:207], v233 offset:17216
	ds_read_b128 v[208:211], v233 offset:17280
	ds_read_b128 v[212:215], v233 offset:17344
	v_mfma_f32_16x16x32_bf16 v[160:163], v[128:131], v[0:3], 0
	v_fma_f32 v216, v168, v178, -v180
	v_fma_f32 v217, v169, v178, -v180
	v_mfma_f32_16x16x32_bf16 v[164:167], v[128:131], v[32:35], 0
	v_fma_f32 v218, v170, v178, -v180
	v_fma_f32 v219, v171, v178, -v180
	v_mfma_f32_16x16x32_bf16 v[160:163], v[132:135], v[4:7], v[160:163]
	v_exp_f32_e32 v216, v216
	v_exp_f32_e32 v217, v217
	v_mfma_f32_16x16x32_bf16 v[164:167], v[132:135], v[36:39], v[164:167]
	v_exp_f32_e32 v218, v218
	v_exp_f32_e32 v219, v219
	v_mfma_f32_16x16x32_bf16 v[160:163], v[136:139], v[8:11], v[160:163]
	v_fma_f32 v220, v172, v179, -v180
	v_fma_f32 v221, v173, v179, -v180
	v_mfma_f32_16x16x32_bf16 v[164:167], v[136:139], v[40:43], v[164:167]
	v_fma_f32 v222, v174, v179, -v180
	v_fma_f32 v223, v175, v179, -v180
	v_mfma_f32_16x16x32_bf16 v[160:163], v[140:143], v[12:15], v[160:163]
	v_exp_f32_e32 v220, v220
	v_exp_f32_e32 v221, v221
	v_mfma_f32_16x16x32_bf16 v[164:167], v[140:143], v[44:47], v[164:167]
	v_exp_f32_e32 v222, v222
	v_exp_f32_e32 v223, v223
	v_mfma_f32_16x16x32_bf16 v[160:163], v[144:147], v[16:19], v[160:163]
	v_add_f32_e32 v176, v176, v216
	v_add_f32_e32 v176, v176, v217
	v_mfma_f32_16x16x32_bf16 v[164:167], v[144:147], v[48:51], v[164:167]
	v_cvt_pk_bf16_f32 v78, v216, v217
	v_add_f32_e32 v176, v176, v218
	v_mfma_f32_16x16x32_bf16 v[160:163], v[148:151], v[20:23], v[160:163]
	v_add_f32_e32 v176, v176, v219
	v_cvt_pk_bf16_f32 v79, v218, v219
	v_mfma_f32_16x16x32_bf16 v[164:167], v[148:151], v[52:55], v[164:167]
	v_add_f32_e32 v177, v177, v220
	v_add_f32_e32 v177, v177, v221
	v_mfma_f32_16x16x32_bf16 v[160:163], v[152:155], v[24:27], v[160:163]
	v_cvt_pk_bf16_f32 v110, v220, v221
	v_add_f32_e32 v177, v177, v222
	v_mfma_f32_16x16x32_bf16 v[164:167], v[152:155], v[56:59], v[164:167]
	v_add_f32_e32 v177, v177, v223
	v_cvt_pk_bf16_f32 v111, v222, v223
	v_mfma_f32_16x16x32_bf16 v[160:163], v[156:159], v[28:31], v[160:163]
	v_mfma_f32_16x16x32_bf16 v[164:167], v[156:159], v[60:63], v[164:167]
	s_waitcnt lgkmcnt(0)
	ds_read_b128 v[128:131], v233 offset:25344
	ds_read_b128 v[132:135], v233 offset:25408
	ds_read_b128 v[136:139], v233 offset:25472
	ds_read_b128 v[140:143], v233 offset:25536
	ds_read_b128 v[144:147], v233 offset:25600
	ds_read_b128 v[148:151], v233 offset:25664
	ds_read_b128 v[152:155], v233 offset:25728
	ds_read_b128 v[156:159], v233 offset:25792
	v_mfma_f32_16x16x32_bf16 v[168:171], v[184:187], v[0:3], 0
	v_fma_f32 v216, v160, v178, -v180
	v_fma_f32 v217, v161, v178, -v180
	v_mfma_f32_16x16x32_bf16 v[172:175], v[184:187], v[32:35], 0
	v_fma_f32 v218, v162, v178, -v180
	v_fma_f32 v219, v163, v178, -v180
	v_mfma_f32_16x16x32_bf16 v[168:171], v[188:191], v[4:7], v[168:171]
	v_exp_f32_e32 v216, v216
	v_exp_f32_e32 v217, v217
	v_mfma_f32_16x16x32_bf16 v[172:175], v[188:191], v[36:39], v[172:175]
	v_exp_f32_e32 v218, v218
	v_exp_f32_e32 v219, v219
	v_mfma_f32_16x16x32_bf16 v[168:171], v[192:195], v[8:11], v[168:171]
	v_fma_f32 v220, v164, v179, -v180
	v_fma_f32 v221, v165, v179, -v180
	v_mfma_f32_16x16x32_bf16 v[172:175], v[192:195], v[40:43], v[172:175]
	v_fma_f32 v222, v166, v179, -v180
	v_fma_f32 v223, v167, v179, -v180
	v_mfma_f32_16x16x32_bf16 v[168:171], v[196:199], v[12:15], v[168:171]
	v_exp_f32_e32 v220, v220
	v_exp_f32_e32 v221, v221
	v_mfma_f32_16x16x32_bf16 v[172:175], v[196:199], v[44:47], v[172:175]
	v_exp_f32_e32 v222, v222
	v_exp_f32_e32 v223, v223
	v_mfma_f32_16x16x32_bf16 v[168:171], v[200:203], v[16:19], v[168:171]
	v_add_f32_e32 v176, v176, v216
	v_add_f32_e32 v176, v176, v217
	v_mfma_f32_16x16x32_bf16 v[172:175], v[200:203], v[48:51], v[172:175]
	v_cvt_pk_bf16_f32 v80, v216, v217
	v_add_f32_e32 v176, v176, v218
	v_mfma_f32_16x16x32_bf16 v[168:171], v[204:207], v[20:23], v[168:171]
	v_add_f32_e32 v176, v176, v219
	v_cvt_pk_bf16_f32 v81, v218, v219
	v_mfma_f32_16x16x32_bf16 v[172:175], v[204:207], v[52:55], v[172:175]
	v_add_f32_e32 v177, v177, v220
	v_add_f32_e32 v177, v177, v221
	v_mfma_f32_16x16x32_bf16 v[168:171], v[208:211], v[24:27], v[168:171]
	v_cvt_pk_bf16_f32 v112, v220, v221
	v_add_f32_e32 v177, v177, v222
	v_mfma_f32_16x16x32_bf16 v[172:175], v[208:211], v[56:59], v[172:175]
	v_add_f32_e32 v177, v177, v223
	v_cvt_pk_bf16_f32 v113, v222, v223
	v_mfma_f32_16x16x32_bf16 v[168:171], v[212:215], v[28:31], v[168:171]
	v_mfma_f32_16x16x32_bf16 v[172:175], v[212:215], v[60:63], v[172:175]
	s_waitcnt lgkmcnt(0)
	ds_read_b128 v[184:187], v233 offset:33792
	ds_read_b128 v[188:191], v233 offset:33856
	ds_read_b128 v[192:195], v233 offset:33920
	ds_read_b128 v[196:199], v233 offset:33984
	ds_read_b128 v[200:203], v233 offset:34048
	ds_read_b128 v[204:207], v233 offset:34112
	ds_read_b128 v[208:211], v233 offset:34176
	ds_read_b128 v[212:215], v233 offset:34240
	v_mfma_f32_16x16x32_bf16 v[160:163], v[128:131], v[0:3], 0
	v_fma_f32 v216, v168, v178, -v180
	v_fma_f32 v217, v169, v178, -v180
	v_mfma_f32_16x16x32_bf16 v[164:167], v[128:131], v[32:35], 0
	v_fma_f32 v218, v170, v178, -v180
	v_fma_f32 v219, v171, v178, -v180
	v_mfma_f32_16x16x32_bf16 v[160:163], v[132:135], v[4:7], v[160:163]
	v_exp_f32_e32 v216, v216
	v_exp_f32_e32 v217, v217
	v_mfma_f32_16x16x32_bf16 v[164:167], v[132:135], v[36:39], v[164:167]
	v_exp_f32_e32 v218, v218
	v_exp_f32_e32 v219, v219
	v_mfma_f32_16x16x32_bf16 v[160:163], v[136:139], v[8:11], v[160:163]
	v_fma_f32 v220, v172, v179, -v180
	v_fma_f32 v221, v173, v179, -v180
	v_mfma_f32_16x16x32_bf16 v[164:167], v[136:139], v[40:43], v[164:167]
	v_fma_f32 v222, v174, v179, -v180
	v_fma_f32 v223, v175, v179, -v180
	v_mfma_f32_16x16x32_bf16 v[160:163], v[140:143], v[12:15], v[160:163]
	v_exp_f32_e32 v220, v220
	v_exp_f32_e32 v221, v221
	v_mfma_f32_16x16x32_bf16 v[164:167], v[140:143], v[44:47], v[164:167]
	v_exp_f32_e32 v222, v222
	v_exp_f32_e32 v223, v223
	v_mfma_f32_16x16x32_bf16 v[160:163], v[144:147], v[16:19], v[160:163]
	v_add_f32_e32 v176, v176, v216
	v_add_f32_e32 v176, v176, v217
	v_mfma_f32_16x16x32_bf16 v[164:167], v[144:147], v[48:51], v[164:167]
	v_cvt_pk_bf16_f32 v82, v216, v217
	v_add_f32_e32 v176, v176, v218
	v_mfma_f32_16x16x32_bf16 v[160:163], v[148:151], v[20:23], v[160:163]
	v_add_f32_e32 v176, v176, v219
	v_cvt_pk_bf16_f32 v83, v218, v219
	v_mfma_f32_16x16x32_bf16 v[164:167], v[148:151], v[52:55], v[164:167]
	v_add_f32_e32 v177, v177, v220
	v_add_f32_e32 v177, v177, v221
	v_mfma_f32_16x16x32_bf16 v[160:163], v[152:155], v[24:27], v[160:163]
	v_cvt_pk_bf16_f32 v114, v220, v221
	v_add_f32_e32 v177, v177, v222
	v_mfma_f32_16x16x32_bf16 v[164:167], v[152:155], v[56:59], v[164:167]
	v_add_f32_e32 v177, v177, v223
	v_cvt_pk_bf16_f32 v115, v222, v223
	v_mfma_f32_16x16x32_bf16 v[160:163], v[156:159], v[28:31], v[160:163]
	v_mfma_f32_16x16x32_bf16 v[164:167], v[156:159], v[60:63], v[164:167]
	s_waitcnt lgkmcnt(0)
	ds_read_b128 v[128:131], v233 offset:42240
	ds_read_b128 v[132:135], v233 offset:42304
	ds_read_b128 v[136:139], v233 offset:42368
	ds_read_b128 v[140:143], v233 offset:42432
	ds_read_b128 v[144:147], v233 offset:42496
	ds_read_b128 v[148:151], v233 offset:42560
	ds_read_b128 v[152:155], v233 offset:42624
	ds_read_b128 v[156:159], v233 offset:42688
	v_mfma_f32_16x16x32_bf16 v[168:171], v[184:187], v[0:3], 0
	v_fma_f32 v216, v160, v178, -v180
	v_fma_f32 v217, v161, v178, -v180
	v_mfma_f32_16x16x32_bf16 v[172:175], v[184:187], v[32:35], 0
	v_fma_f32 v218, v162, v178, -v180
	v_fma_f32 v219, v163, v178, -v180
	v_mfma_f32_16x16x32_bf16 v[168:171], v[188:191], v[4:7], v[168:171]
	v_exp_f32_e32 v216, v216
	v_exp_f32_e32 v217, v217
	v_mfma_f32_16x16x32_bf16 v[172:175], v[188:191], v[36:39], v[172:175]
	v_exp_f32_e32 v218, v218
	v_exp_f32_e32 v219, v219
	v_mfma_f32_16x16x32_bf16 v[168:171], v[192:195], v[8:11], v[168:171]
	v_fma_f32 v220, v164, v179, -v180
	v_fma_f32 v221, v165, v179, -v180
	v_mfma_f32_16x16x32_bf16 v[172:175], v[192:195], v[40:43], v[172:175]
	v_fma_f32 v222, v166, v179, -v180
	v_fma_f32 v223, v167, v179, -v180
	v_mfma_f32_16x16x32_bf16 v[168:171], v[196:199], v[12:15], v[168:171]
	v_exp_f32_e32 v220, v220
	v_exp_f32_e32 v221, v221
	v_mfma_f32_16x16x32_bf16 v[172:175], v[196:199], v[44:47], v[172:175]
	v_exp_f32_e32 v222, v222
	v_exp_f32_e32 v223, v223
	v_mfma_f32_16x16x32_bf16 v[168:171], v[200:203], v[16:19], v[168:171]
	v_add_f32_e32 v176, v176, v216
	v_add_f32_e32 v176, v176, v217
	v_mfma_f32_16x16x32_bf16 v[172:175], v[200:203], v[48:51], v[172:175]
	v_cvt_pk_bf16_f32 v84, v216, v217
	v_add_f32_e32 v176, v176, v218
	v_mfma_f32_16x16x32_bf16 v[168:171], v[204:207], v[20:23], v[168:171]
	v_add_f32_e32 v176, v176, v219
	v_cvt_pk_bf16_f32 v85, v218, v219
	v_mfma_f32_16x16x32_bf16 v[172:175], v[204:207], v[52:55], v[172:175]
	v_add_f32_e32 v177, v177, v220
	v_add_f32_e32 v177, v177, v221
	v_mfma_f32_16x16x32_bf16 v[168:171], v[208:211], v[24:27], v[168:171]
	v_cvt_pk_bf16_f32 v116, v220, v221
	v_add_f32_e32 v177, v177, v222
	v_mfma_f32_16x16x32_bf16 v[172:175], v[208:211], v[56:59], v[172:175]
	v_add_f32_e32 v177, v177, v223
	v_cvt_pk_bf16_f32 v117, v222, v223
	v_mfma_f32_16x16x32_bf16 v[168:171], v[212:215], v[28:31], v[168:171]
	v_mfma_f32_16x16x32_bf16 v[172:175], v[212:215], v[60:63], v[172:175]
	s_waitcnt lgkmcnt(0)
	ds_read_b128 v[184:187], v233 offset:50688
	ds_read_b128 v[188:191], v233 offset:50752
	ds_read_b128 v[192:195], v233 offset:50816
	ds_read_b128 v[196:199], v233 offset:50880
	ds_read_b128 v[200:203], v233 offset:50944
	ds_read_b128 v[204:207], v233 offset:51008
	ds_read_b128 v[208:211], v233 offset:51072
	ds_read_b128 v[212:215], v233 offset:51136
	v_mfma_f32_16x16x32_bf16 v[160:163], v[128:131], v[0:3], 0
	v_fma_f32 v216, v168, v178, -v180
	v_fma_f32 v217, v169, v178, -v180
	v_mfma_f32_16x16x32_bf16 v[164:167], v[128:131], v[32:35], 0
	v_fma_f32 v218, v170, v178, -v180
	v_fma_f32 v219, v171, v178, -v180
	v_mfma_f32_16x16x32_bf16 v[160:163], v[132:135], v[4:7], v[160:163]
	v_exp_f32_e32 v216, v216
	v_exp_f32_e32 v217, v217
	v_mfma_f32_16x16x32_bf16 v[164:167], v[132:135], v[36:39], v[164:167]
	v_exp_f32_e32 v218, v218
	v_exp_f32_e32 v219, v219
	v_mfma_f32_16x16x32_bf16 v[160:163], v[136:139], v[8:11], v[160:163]
	v_fma_f32 v220, v172, v179, -v180
	v_fma_f32 v221, v173, v179, -v180
	v_mfma_f32_16x16x32_bf16 v[164:167], v[136:139], v[40:43], v[164:167]
	v_fma_f32 v222, v174, v179, -v180
	v_fma_f32 v223, v175, v179, -v180
	v_mfma_f32_16x16x32_bf16 v[160:163], v[140:143], v[12:15], v[160:163]
	v_exp_f32_e32 v220, v220
	v_exp_f32_e32 v221, v221
	v_mfma_f32_16x16x32_bf16 v[164:167], v[140:143], v[44:47], v[164:167]
	v_exp_f32_e32 v222, v222
	v_exp_f32_e32 v223, v223
	v_mfma_f32_16x16x32_bf16 v[160:163], v[144:147], v[16:19], v[160:163]
	v_add_f32_e32 v176, v176, v216
	v_add_f32_e32 v176, v176, v217
	v_mfma_f32_16x16x32_bf16 v[164:167], v[144:147], v[48:51], v[164:167]
	v_cvt_pk_bf16_f32 v86, v216, v217
	v_add_f32_e32 v176, v176, v218
	v_mfma_f32_16x16x32_bf16 v[160:163], v[148:151], v[20:23], v[160:163]
	v_add_f32_e32 v176, v176, v219
	v_cvt_pk_bf16_f32 v87, v218, v219
	v_mfma_f32_16x16x32_bf16 v[164:167], v[148:151], v[52:55], v[164:167]
	v_add_f32_e32 v177, v177, v220
	v_add_f32_e32 v177, v177, v221
	v_mfma_f32_16x16x32_bf16 v[160:163], v[152:155], v[24:27], v[160:163]
	v_cvt_pk_bf16_f32 v118, v220, v221
	v_add_f32_e32 v177, v177, v222
	v_mfma_f32_16x16x32_bf16 v[164:167], v[152:155], v[56:59], v[164:167]
	v_add_f32_e32 v177, v177, v223
	v_cvt_pk_bf16_f32 v119, v222, v223
	v_mfma_f32_16x16x32_bf16 v[160:163], v[156:159], v[28:31], v[160:163]
	v_mfma_f32_16x16x32_bf16 v[164:167], v[156:159], v[60:63], v[164:167]
	s_waitcnt lgkmcnt(0)
	v_add_u32_e32 v233, 59136, v233
	ds_read_b128 v[128:131], v233 offset:0
	ds_read_b128 v[132:135], v233 offset:64
	ds_read_b128 v[136:139], v233 offset:128
	ds_read_b128 v[140:143], v233 offset:192
	ds_read_b128 v[144:147], v233 offset:256
	ds_read_b128 v[148:151], v233 offset:320
	ds_read_b128 v[152:155], v233 offset:384
	ds_read_b128 v[156:159], v233 offset:448
	v_mfma_f32_16x16x32_bf16 v[168:171], v[184:187], v[0:3], 0
	v_fma_f32 v216, v160, v178, -v180
	v_fma_f32 v217, v161, v178, -v180
	v_mfma_f32_16x16x32_bf16 v[172:175], v[184:187], v[32:35], 0
	v_fma_f32 v218, v162, v178, -v180
	v_fma_f32 v219, v163, v178, -v180
	v_mfma_f32_16x16x32_bf16 v[168:171], v[188:191], v[4:7], v[168:171]
	v_exp_f32_e32 v216, v216
	v_exp_f32_e32 v217, v217
	v_mfma_f32_16x16x32_bf16 v[172:175], v[188:191], v[36:39], v[172:175]
	v_exp_f32_e32 v218, v218
	v_exp_f32_e32 v219, v219
	v_mfma_f32_16x16x32_bf16 v[168:171], v[192:195], v[8:11], v[168:171]
	v_fma_f32 v220, v164, v179, -v180
	v_fma_f32 v221, v165, v179, -v180
	v_mfma_f32_16x16x32_bf16 v[172:175], v[192:195], v[40:43], v[172:175]
	v_fma_f32 v222, v166, v179, -v180
	v_fma_f32 v223, v167, v179, -v180
	v_mfma_f32_16x16x32_bf16 v[168:171], v[196:199], v[12:15], v[168:171]
	v_exp_f32_e32 v220, v220
	v_exp_f32_e32 v221, v221
	v_mfma_f32_16x16x32_bf16 v[172:175], v[196:199], v[44:47], v[172:175]
	v_exp_f32_e32 v222, v222
	v_exp_f32_e32 v223, v223
	v_mfma_f32_16x16x32_bf16 v[168:171], v[200:203], v[16:19], v[168:171]
	v_add_f32_e32 v176, v176, v216
	v_add_f32_e32 v176, v176, v217
	v_mfma_f32_16x16x32_bf16 v[172:175], v[200:203], v[48:51], v[172:175]
	v_cvt_pk_bf16_f32 v88, v216, v217
	v_add_f32_e32 v176, v176, v218
	v_mfma_f32_16x16x32_bf16 v[168:171], v[204:207], v[20:23], v[168:171]
	v_add_f32_e32 v176, v176, v219
	v_cvt_pk_bf16_f32 v89, v218, v219
	v_mfma_f32_16x16x32_bf16 v[172:175], v[204:207], v[52:55], v[172:175]
	v_add_f32_e32 v177, v177, v220
	v_add_f32_e32 v177, v177, v221
	v_mfma_f32_16x16x32_bf16 v[168:171], v[208:211], v[24:27], v[168:171]
	v_cvt_pk_bf16_f32 v120, v220, v221
	v_add_f32_e32 v177, v177, v222
	v_mfma_f32_16x16x32_bf16 v[172:175], v[208:211], v[56:59], v[172:175]
	v_add_f32_e32 v177, v177, v223
	v_cvt_pk_bf16_f32 v121, v222, v223
	v_mfma_f32_16x16x32_bf16 v[168:171], v[212:215], v[28:31], v[168:171]
	v_mfma_f32_16x16x32_bf16 v[172:175], v[212:215], v[60:63], v[172:175]
	s_waitcnt lgkmcnt(0)
	ds_read_b128 v[184:187], v233 offset:8448
	ds_read_b128 v[188:191], v233 offset:8512
	ds_read_b128 v[192:195], v233 offset:8576
	ds_read_b128 v[196:199], v233 offset:8640
	ds_read_b128 v[200:203], v233 offset:8704
	ds_read_b128 v[204:207], v233 offset:8768
	ds_read_b128 v[208:211], v233 offset:8832
	ds_read_b128 v[212:215], v233 offset:8896
	v_mfma_f32_16x16x32_bf16 v[160:163], v[128:131], v[0:3], 0
	v_fma_f32 v216, v168, v178, -v180
	v_fma_f32 v217, v169, v178, -v180
	v_mfma_f32_16x16x32_bf16 v[164:167], v[128:131], v[32:35], 0
	v_fma_f32 v218, v170, v178, -v180
	v_fma_f32 v219, v171, v178, -v180
	v_mfma_f32_16x16x32_bf16 v[160:163], v[132:135], v[4:7], v[160:163]
	v_exp_f32_e32 v216, v216
	v_exp_f32_e32 v217, v217
	v_mfma_f32_16x16x32_bf16 v[164:167], v[132:135], v[36:39], v[164:167]
	v_exp_f32_e32 v218, v218
	v_exp_f32_e32 v219, v219
	v_mfma_f32_16x16x32_bf16 v[160:163], v[136:139], v[8:11], v[160:163]
	v_fma_f32 v220, v172, v179, -v180
	v_fma_f32 v221, v173, v179, -v180
	v_mfma_f32_16x16x32_bf16 v[164:167], v[136:139], v[40:43], v[164:167]
	v_fma_f32 v222, v174, v179, -v180
	v_fma_f32 v223, v175, v179, -v180
	v_mfma_f32_16x16x32_bf16 v[160:163], v[140:143], v[12:15], v[160:163]
	v_exp_f32_e32 v220, v220
	v_exp_f32_e32 v221, v221
	v_mfma_f32_16x16x32_bf16 v[164:167], v[140:143], v[44:47], v[164:167]
	v_exp_f32_e32 v222, v222
	v_exp_f32_e32 v223, v223
	v_mfma_f32_16x16x32_bf16 v[160:163], v[144:147], v[16:19], v[160:163]
	v_add_f32_e32 v176, v176, v216
	v_add_f32_e32 v176, v176, v217
	v_mfma_f32_16x16x32_bf16 v[164:167], v[144:147], v[48:51], v[164:167]
	v_cvt_pk_bf16_f32 v90, v216, v217
	v_add_f32_e32 v176, v176, v218
	v_mfma_f32_16x16x32_bf16 v[160:163], v[148:151], v[20:23], v[160:163]
	v_add_f32_e32 v176, v176, v219
	v_cvt_pk_bf16_f32 v91, v218, v219
	v_mfma_f32_16x16x32_bf16 v[164:167], v[148:151], v[52:55], v[164:167]
	v_add_f32_e32 v177, v177, v220
	v_add_f32_e32 v177, v177, v221
	v_mfma_f32_16x16x32_bf16 v[160:163], v[152:155], v[24:27], v[160:163]
	v_cvt_pk_bf16_f32 v122, v220, v221
	v_add_f32_e32 v177, v177, v222
	v_mfma_f32_16x16x32_bf16 v[164:167], v[152:155], v[56:59], v[164:167]
	v_add_f32_e32 v177, v177, v223
	v_cvt_pk_bf16_f32 v123, v222, v223
	v_mfma_f32_16x16x32_bf16 v[160:163], v[156:159], v[28:31], v[160:163]
	v_mfma_f32_16x16x32_bf16 v[164:167], v[156:159], v[60:63], v[164:167]
	s_waitcnt lgkmcnt(0)
	s_nop 6
	v_mfma_f32_16x16x32_bf16 v[168:171], v[184:187], v[0:3], 0
	v_fma_f32 v216, v160, v178, -v180
	v_fma_f32 v217, v161, v178, -v180
	v_mfma_f32_16x16x32_bf16 v[172:175], v[184:187], v[32:35], 0
	v_fma_f32 v218, v162, v178, -v180
	v_fma_f32 v219, v163, v178, -v180
	v_mfma_f32_16x16x32_bf16 v[168:171], v[188:191], v[4:7], v[168:171]
	v_exp_f32_e32 v216, v216
	v_exp_f32_e32 v217, v217
	v_mfma_f32_16x16x32_bf16 v[172:175], v[188:191], v[36:39], v[172:175]
	v_exp_f32_e32 v218, v218
	v_exp_f32_e32 v219, v219
	v_mfma_f32_16x16x32_bf16 v[168:171], v[192:195], v[8:11], v[168:171]
	v_fma_f32 v220, v164, v179, -v180
	v_fma_f32 v221, v165, v179, -v180
	v_mfma_f32_16x16x32_bf16 v[172:175], v[192:195], v[40:43], v[172:175]
	v_fma_f32 v222, v166, v179, -v180
	v_fma_f32 v223, v167, v179, -v180
	v_mfma_f32_16x16x32_bf16 v[168:171], v[196:199], v[12:15], v[168:171]
	v_exp_f32_e32 v220, v220
	v_exp_f32_e32 v221, v221
	v_mfma_f32_16x16x32_bf16 v[172:175], v[196:199], v[44:47], v[172:175]
	v_exp_f32_e32 v222, v222
	v_exp_f32_e32 v223, v223
	v_mfma_f32_16x16x32_bf16 v[168:171], v[200:203], v[16:19], v[168:171]
	v_add_f32_e32 v176, v176, v216
	v_add_f32_e32 v176, v176, v217
	v_mfma_f32_16x16x32_bf16 v[172:175], v[200:203], v[48:51], v[172:175]
	v_cvt_pk_bf16_f32 v92, v216, v217
	v_add_f32_e32 v176, v176, v218
	v_mfma_f32_16x16x32_bf16 v[168:171], v[204:207], v[20:23], v[168:171]
	v_add_f32_e32 v176, v176, v219
	v_cvt_pk_bf16_f32 v93, v218, v219
	v_mfma_f32_16x16x32_bf16 v[172:175], v[204:207], v[52:55], v[172:175]
	v_add_f32_e32 v177, v177, v220
	v_add_f32_e32 v177, v177, v221
	v_mfma_f32_16x16x32_bf16 v[168:171], v[208:211], v[24:27], v[168:171]
	v_cvt_pk_bf16_f32 v124, v220, v221
	v_add_f32_e32 v177, v177, v222
	v_mfma_f32_16x16x32_bf16 v[172:175], v[208:211], v[56:59], v[172:175]
	v_add_f32_e32 v177, v177, v223
	v_cvt_pk_bf16_f32 v125, v222, v223
	v_mfma_f32_16x16x32_bf16 v[168:171], v[212:215], v[28:31], v[168:171]
	v_mfma_f32_16x16x32_bf16 v[172:175], v[212:215], v[60:63], v[172:175]
	s_nop 7
	v_fma_f32 v216, v168, v178, -v180
	v_fma_f32 v217, v169, v178, -v180
	v_fma_f32 v218, v170, v178, -v180
	v_fma_f32 v219, v171, v178, -v180
	v_exp_f32_e32 v216, v216
	v_exp_f32_e32 v217, v217
	v_exp_f32_e32 v218, v218
	v_exp_f32_e32 v219, v219
	v_fma_f32 v220, v172, v179, -v180
	v_fma_f32 v221, v173, v179, -v180
	v_fma_f32 v222, v174, v179, -v180
	v_fma_f32 v223, v175, v179, -v180
	v_exp_f32_e32 v220, v220
	v_exp_f32_e32 v221, v221
	v_exp_f32_e32 v222, v222
	v_exp_f32_e32 v223, v223
	v_add_f32_e32 v176, v176, v216
	v_add_f32_e32 v176, v176, v217
	v_cvt_pk_bf16_f32 v94, v216, v217
	v_add_f32_e32 v176, v176, v218
	v_add_f32_e32 v176, v176, v219
	v_cvt_pk_bf16_f32 v95, v218, v219
	v_add_f32_e32 v177, v177, v220
	v_add_f32_e32 v177, v177, v221
	v_cvt_pk_bf16_f32 v126, v220, v221
	v_add_f32_e32 v177, v177, v222
	v_add_f32_e32 v177, v177, v223
	v_cvt_pk_bf16_f32 v127, v222, v223
	s_barrier
	global_load_dwordx4 v[128:131], v225, s[8:9]
	s_add_u32 s8, s8, 0x14000
	s_addc_u32 s9, s9, 0
	global_load_dwordx4 v[132:135], v225, s[8:9]
	s_add_u32 s8, s8, 0x14000
	s_addc_u32 s9, s9, 0
	global_load_dwordx4 v[136:139], v225, s[8:9]
	s_add_u32 s8, s8, 0x14000
	s_addc_u32 s9, s9, 0
	global_load_dwordx4 v[140:143], v225, s[8:9]
	s_add_u32 s8, s8, 0x14000
	s_addc_u32 s9, s9, 0
	global_load_dwordx4 v[144:147], v225, s[8:9]
	s_add_u32 s8, s8, 0x14000
	s_addc_u32 s9, s9, 0
	global_load_dwordx4 v[148:151], v225, s[8:9]
	s_add_u32 s8, s8, 0x14000
	s_addc_u32 s9, s9, 0
	global_load_dwordx4 v[152:155], v225, s[8:9]
	s_add_u32 s8, s8, 0x14000
	s_addc_u32 s9, s9, 0
	global_load_dwordx4 v[156:159], v225, s[8:9]
	s_add_u32 s8, s8, 0x14000
	s_addc_u32 s9, s9, 0
	global_load_dwordx4 v[184:187], v225, s[8:9]
	s_add_u32 s8, s8, 0x14000
	s_addc_u32 s9, s9, 0
	global_load_dwordx4 v[188:191], v225, s[8:9]
	s_add_u32 s8, s8, 0x14000
	s_addc_u32 s9, s9, 0
	global_load_dwordx4 v[192:195], v225, s[8:9]
	s_add_u32 s8, s8, 0x14000
	s_addc_u32 s9, s9, 0
	global_load_dwordx4 v[196:199], v225, s[8:9]
	s_add_u32 s8, s8, 0x14000
	s_addc_u32 s9, s9, 0
	global_load_dwordx4 v[200:203], v225, s[8:9]
	s_add_u32 s8, s8, 0x14000
	s_addc_u32 s9, s9, 0
	global_load_dwordx4 v[204:207], v225, s[8:9]
	s_add_u32 s8, s8, 0x14000
	s_addc_u32 s9, s9, 0
	global_load_dwordx4 v[208:211], v225, s[8:9]
	s_add_u32 s8, s8, 0x14000
	s_addc_u32 s9, s9, 0
	global_load_dwordx4 v[212:215], v225, s[8:9]
	s_add_i32 s16, s69, s86
	s_cmpk_lt_i32 s16, 0x300
	s_cselect_b32 s16, s16, s69
	s_lshr_b32 s0, s16, 6
	s_mul_i32 s0, s0, 0x5556
	s_lshr_b32 s0, s0, 16
	s_mul_i32 s1, s0, 192
	s_sub_i32 s1, s16, s1
	s_lshl_b32 s11, s1, 19
	s_lshl_b32 s12, s0, 9
	s_add_u32 s11, s11, s12
	s_add_u32 s12, s11, 0xf000000
	s_add_u32 s10, s4, s12
	s_addc_u32 s11, s5, 0
	s_lshl_b32 s12, s1, 12
	s_lshl_b32 s13, s0, 2
	s_add_u32 s12, s12, s13
	s_add_u32 s12, s12, 0x1fa60000
	s_add_u32 s12, s4, s12
	s_addc_u32 s13, s5, 0
	global_load_dwordx4 v[0:3], v228, s[10:11] offset:0
	global_load_dwordx4 v[4:7], v228, s[10:11] offset:64
	global_load_dwordx4 v[8:11], v228, s[10:11] offset:128
	global_load_dwordx4 v[12:15], v228, s[10:11] offset:192
	global_load_dwordx4 v[16:19], v228, s[10:11] offset:256
	global_load_dwordx4 v[20:23], v228, s[10:11] offset:320
	global_load_dwordx4 v[24:27], v228, s[10:11] offset:384
	global_load_dwordx4 v[28:31], v228, s[10:11] offset:448
	global_load_dwordx4 v[32:35], v229, s[10:11] offset:0
	global_load_dwordx4 v[36:39], v229, s[10:11] offset:64
	global_load_dwordx4 v[40:43], v229, s[10:11] offset:128
	global_load_dwordx4 v[44:47], v229, s[10:11] offset:192
	global_load_dwordx4 v[48:51], v229, s[10:11] offset:256
	global_load_dwordx4 v[52:55], v229, s[10:11] offset:320
	global_load_dwordx4 v[56:59], v229, s[10:11] offset:384
	global_load_dwordx4 v[60:63], v229, s[10:11] offset:448
	global_load_dword v247, v230, s[12:13]
	global_load_dword v248, v230, s[12:13] offset:2048
	ds_bpermute_b32 v242, v236, v176
	s_waitcnt lgkmcnt(0)
	v_add_f32_e32 v176, v176, v242
	ds_bpermute_b32 v242, v237, v176
	s_waitcnt lgkmcnt(0)
	v_add_f32_e32 v176, v176, v242
	ds_bpermute_b32 v242, v236, v177
	s_waitcnt lgkmcnt(0)
	v_add_f32_e32 v177, v177, v242
	ds_bpermute_b32 v242, v237, v177
	s_waitcnt lgkmcnt(0)
	v_add_f32_e32 v177, v177, v242
	v_rcp_f32_e32 v240, v176
	v_rcp_f32_e32 v241, v177
	s_waitcnt vmcnt(30)
	ds_write_b128 v250, v[128:131] offset:0
	ds_write_b128 v250, v[132:135] offset:4224
	ds_write_b128 v250, v[136:139] offset:16896
	ds_write_b128 v250, v[140:143] offset:21120
	s_waitcnt vmcnt(26)
	ds_write_b128 v250, v[144:147] offset:33792
	ds_write_b128 v250, v[148:151] offset:38016
	ds_write_b128 v250, v[152:155] offset:50688
	ds_write_b128 v250, v[156:159] offset:54912
	s_waitcnt vmcnt(22)
	ds_write_b128 v251, v[184:187] offset:0
	ds_write_b128 v251, v[188:191] offset:4224
	ds_write_b128 v251, v[192:195] offset:16896
	ds_write_b128 v251, v[196:199] offset:21120
	s_waitcnt vmcnt(18)
	ds_write_b128 v251, v[200:203] offset:33792
	ds_write_b128 v251, v[204:207] offset:38016
	ds_write_b128 v251, v[208:211] offset:50688
	ds_write_b128 v251, v[212:215] offset:54912
	s_waitcnt lgkmcnt(0)
	s_barrier
	s_mov_b32 s18, 0
	v_mov_b32_e32 v234, v232
	v_add_u32_e32 v235, 16896, v232
	ds_read_b64 v[128:129], v234 offset:0
	ds_read_b64 v[130:131], v234 offset:32
	ds_read_b64 v[132:133], v234 offset:64
	ds_read_b64 v[134:135], v234 offset:96
	ds_read_b64 v[136:137], v234 offset:128
	ds_read_b64 v[138:139], v234 offset:160
	ds_read_b64 v[140:141], v234 offset:192
	ds_read_b64 v[142:143], v234 offset:224
	ds_read_b64 v[144:145], v234 offset:256
	ds_read_b64 v[146:147], v234 offset:288
	ds_read_b64 v[148:149], v234 offset:320
	ds_read_b64 v[150:151], v234 offset:352
.Lxa_pv:
	ds_read_b64 v[152:153], v234 offset:384
	ds_read_b64 v[154:155], v234 offset:416
	s_waitcnt lgkmcnt(12)
	v_mfma_f32_16x16x32_bf16 v[160:163], v[128:131], v[64:67], 0
	v_mfma_f32_16x16x32_bf16 v[164:167], v[128:131], v[96:99], 0
	ds_read_b64 v[156:157], v234 offset:448
	ds_read_b64 v[158:159], v234 offset:480
	s_waitcnt lgkmcnt(12)
	v_mfma_f32_16x16x32_bf16 v[160:163], v[132:135], v[68:71], v[160:163]
	v_mfma_f32_16x16x32_bf16 v[164:167], v[132:135], v[100:103], v[164:167]
	ds_read_b64 v[128:129], v234 offset:8448
	ds_read_b64 v[130:131], v234 offset:8480
	s_waitcnt lgkmcnt(12)
	v_mfma_f32_16x16x32_bf16 v[160:163], v[136:139], v[72:75], v[160:163]
	v_mfma_f32_16x16x32_bf16 v[164:167], v[136:139], v[104:107], v[164:167]
	ds_read_b64 v[132:133], v234 offset:8512
	ds_read_b64 v[134:135], v234 offset:8544
	s_waitcnt lgkmcnt(12)
	v_mfma_f32_16x16x32_bf16 v[160:163], v[140:143], v[76:79], v[160:163]
	v_mfma_f32_16x16x32_bf16 v[164:167], v[140:143], v[108:111], v[164:167]
	ds_read_b64 v[136:137], v234 offset:8576
	ds_read_b64 v[138:139], v234 offset:8608
	s_waitcnt lgkmcnt(12)
	v_mfma_f32_16x16x32_bf16 v[160:163], v[144:147], v[80:83], v[160:163]
	v_mfma_f32_16x16x32_bf16 v[164:167], v[144:147], v[112:115], v[164:167]
	ds_read_b64 v[140:141], v234 offset:8640
	ds_read_b64 v[142:143], v234 offset:8672
	s_waitcnt lgkmcnt(12)
	v_mfma_f32_16x16x32_bf16 v[160:163], v[148:151], v[84:87], v[160:163]
	v_mfma_f32_16x16x32_bf16 v[164:167], v[148:151], v[116:119], v[164:167]
	ds_read_b64 v[144:145], v234 offset:8704
	ds_read_b64 v[146:147], v234 offset:8736
	s_waitcnt lgkmcnt(12)
	v_mfma_f32_16x16x32_bf16 v[160:163], v[152:155], v[88:91], v[160:163]
	v_mfma_f32_16x16x32_bf16 v[164:167], v[152:155], v[120:123], v[164:167]
	ds_read_b64 v[148:149], v234 offset:8768
	ds_read_b64 v[150:151], v234 offset:8800
	s_waitcnt lgkmcnt(12)
	v_mfma_f32_16x16x32_bf16 v[160:163], v[156:159], v[92:95], v[160:163]
	v_mfma_f32_16x16x32_bf16 v[164:167], v[156:159], v[124:127], v[164:167]
	ds_read_b64 v[152:153], v234 offset:8832
	ds_read_b64 v[154:155], v234 offset:8864
	s_waitcnt lgkmcnt(12)
	v_mfma_f32_16x16x32_bf16 v[168:171], v[128:131], v[64:67], 0
	v_mfma_f32_16x16x32_bf16 v[172:175], v[128:131], v[96:99], 0
	ds_read_b64 v[156:157], v234 offset:8896
	ds_read_b64 v[158:159], v234 offset:8928
	s_waitcnt lgkmcnt(12)
	v_mfma_f32_16x16x32_bf16 v[168:171], v[132:135], v[68:71], v[168:171]
	v_mfma_f32_16x16x32_bf16 v[172:175], v[132:135], v[100:103], v[172:175]
	ds_read_b64 v[128:129], v235 offset:0
	ds_read_b64 v[130:131], v235 offset:32
	s_waitcnt lgkmcnt(12)
	v_mfma_f32_16x16x32_bf16 v[168:171], v[136:139], v[72:75], v[168:171]
	v_mfma_f32_16x16x32_bf16 v[172:175], v[136:139], v[104:107], v[172:175]
	ds_read_b64 v[132:133], v235 offset:64
	ds_read_b64 v[134:135], v235 offset:96
	s_waitcnt lgkmcnt(12)
	v_mfma_f32_16x16x32_bf16 v[168:171], v[140:143], v[76:79], v[168:171]
	v_mfma_f32_16x16x32_bf16 v[172:175], v[140:143], v[108:111], v[172:175]
	ds_read_b64 v[136:137], v235 offset:128
	ds_read_b64 v[138:139], v235 offset:160
	s_waitcnt lgkmcnt(12)
	v_mfma_f32_16x16x32_bf16 v[168:171], v[144:147], v[80:83], v[168:171]
	v_mfma_f32_16x16x32_bf16 v[172:175], v[144:147], v[112:115], v[172:175]
	ds_read_b64 v[140:141], v235 offset:192
	ds_read_b64 v[142:143], v235 offset:224
	s_waitcnt lgkmcnt(12)
	v_mfma_f32_16x16x32_bf16 v[168:171], v[148:151], v[84:87], v[168:171]
	v_mfma_f32_16x16x32_bf16 v[172:175], v[148:151], v[116:119], v[172:175]
	ds_read_b64 v[144:145], v235 offset:256
	ds_read_b64 v[146:147], v235 offset:288
	s_waitcnt lgkmcnt(12)
	v_mfma_f32_16x16x32_bf16 v[168:171], v[152:155], v[88:91], v[168:171]
	v_mfma_f32_16x16x32_bf16 v[172:175], v[152:155], v[120:123], v[172:175]
	ds_read_b64 v[148:149], v235 offset:320
	ds_read_b64 v[150:151], v235 offset:352
	s_waitcnt lgkmcnt(12)
	v_mfma_f32_16x16x32_bf16 v[168:171], v[156:159], v[92:95], v[168:171]
	v_mfma_f32_16x16x32_bf16 v[172:175], v[156:159], v[124:127], v[172:175]
	s_add_i32 s18, s18, 1
	s_add_i32 s19, s18, 1
	s_and_b32 s19, s19, 7
	s_mul_i32 s19, s19, 16896
	s_nop 3
	v_mul_f32_e32 v160, v160, v240
	v_mul_f32_e32 v161, v161, v240
	v_mul_f32_e32 v162, v162, v240
	v_mul_f32_e32 v163, v163, v240
	v_mul_f32_e32 v168, v168, v240
	v_mul_f32_e32 v169, v169, v240
	v_mul_f32_e32 v170, v170, v240
	v_mul_f32_e32 v171, v171, v240
	v_cvt_pk_bf16_f32 v216, v160, v161
	v_cvt_pk_bf16_f32 v217, v162, v163
	v_cvt_pk_bf16_f32 v218, v168, v169
	v_cvt_pk_bf16_f32 v219, v170, v171
	v_mul_f32_e32 v164, v164, v241
	v_mul_f32_e32 v165, v165, v241
	v_mul_f32_e32 v166, v166, v241
	v_mul_f32_e32 v167, v167, v241
	v_mul_f32_e32 v172, v172, v241
	v_mul_f32_e32 v173, v173, v241
	v_mul_f32_e32 v174, v174, v241
	v_mul_f32_e32 v175, v175, v241
	v_cvt_pk_bf16_f32 v220, v164, v165
	v_cvt_pk_bf16_f32 v221, v166, v167
	v_cvt_pk_bf16_f32 v222, v172, v173
	v_cvt_pk_bf16_f32 v223, v174, v175
	global_store_dwordx4 v228, v[216:219], s[14:15]
	global_store_dwordx4 v229, v[220:223], s[14:15]
	s_add_u32 s14, s14, 64
	s_addc_u32 s15, s15, 0
	v_mov_b32_e32 v234, v235
	v_add_u32_e32 v235, s19, v232
	s_cmp_lt_u32 s18, 8
	s_cbranch_scc1 .Lxa_pv
	s_waitcnt lgkmcnt(0)
	s_add_i32 s69, s69, s86
	s_cmpk_lt_i32 s69, 0x300
	s_barrier
	s_cbranch_scc1 .Lxa_unit
